# GEMM K-loops: removed the redundant back-to-back s_setprio 0 / s_setprio 1 pair in the middle of each 32-MFMA block (20 sites)
# baseline (speedup 1.0000x reference)
; #define PG8_STAGE(bufoff, gbase, voff) do { _Pragma("unroll") for (int _i = 0; _i < 2; ++_i) \
;         __builtin_amdgcn_global_load_lds((const unsigned*)((const char*)(gbase) + (voff)[_i]), (LAS unsigned*)(lds + (bufoff) + ldsw + _i * 8192), 16, 0, 0); } while (0)
; #define PG8_LDA(dst, b, h) do { _Pragma("unroll") for (int m = 0; m < 4; ++m) _Pragma("unroll") for (int k = 0; k < 2; ++k) dst[m][k] = *(const LAS bf16x8*)(lds + PG8_SA(b, h) + aoff + m * 2048 + k * 1024); } while (0)
; #define PG8_LDB(dst, b, h) do { _Pragma("unroll") for (int n = 0; n < 2; ++n) _Pragma("unroll") for (int k = 0; k < 2; ++k) dst[n][k] = *(const LAS bf16x8*)(lds + PG8_SB(b, h) + boff + n * 2048 + k * 1024); } while (0)
; #define PG8_MMA(ai, bj, At, Bt) do { __builtin_amdgcn_s_setprio(1); _Pragma("unroll") for (int m = 0; m < 4; ++m) _Pragma("unroll") for (int n = 0; n < 2; ++n) _Pragma("unroll") for (int k = 0; k < 2; ++k) \
;         acc[ai][bj][m][n] = __builtin_amdgcn_mfma_f32_16x16x32_bf16(Bt[n][k], At[m][k], acc[ai][bj][m][n], 0, 0, 0); __builtin_amdgcn_s_setprio(0); } while (0)
; #define PG8_WAIT_V(n) asm volatile("s_waitcnt vmcnt(" #n ")" ::: "memory")
; #define PG8_WAIT_L(n) asm volatile("s_waitcnt lgkmcnt(" #n ")" ::: "memory")
; #define PG8_BAR __builtin_amdgcn_s_barrier()
; #define PG8_SCHED __builtin_amdgcn_sched_barrier(0)
; template <class Epi, bool ALIGN_EPI = true, bool SP2 = true>
; DI void gemm_phase(LAS unsigned char* lds, const Gemm g, const StaticOrder& S, const Epi& E) {
;     ...
;             PG8_LDB(B0, 0, 0); PG8_LDB(B1, 0, 1); PG8_SCHED; PG8_LDA(At, 0, 0); PG8_STAGE(PG8_SA(1, 1), a1 + hstepA, voffA);
;             PG8_WAIT_V(8); PG8_WAIT_L(0); PG8_BAR; PG8_MMA(0, 0, At, B0); PG8_MMA(0, 1, At, B1); PG8_BAR; PG8_SCHED;
;             PG8_LDA(At, 0, 1); PG8_STAGE(PG8_SB(0, 0), b2, voffB); PG8_STAGE(PG8_SB(0, 1), b2 + hstepB, voffB); PG8_STAGE(PG8_SA(0, 0), a2, voffA);
;             PG8_WAIT_V(8); PG8_WAIT_L(0); PG8_BAR; PG8_MMA(1, 0, At, B0); PG8_MMA(1, 1, At, B1); PG8_BAR; PG8_SCHED;
.LBB0_261:
	ds_read_b128 v[150:153], v147
	ds_read_b128 v[154:157], v147 offset:1024
	ds_read_b128 v[158:161], v147 offset:2048
	ds_read_b128 v[162:165], v147 offset:3072
	ds_read_b128 v[166:169], v148
	ds_read_b128 v[170:173], v148 offset:1024
	ds_read_b128 v[174:177], v148 offset:2048
	ds_read_b128 v[178:181], v148 offset:3072
	s_add_u32 s46, s34, 0xfff00080
	s_addc_u32 s47, s35, -1
	s_cmp_eq_u32 s78, 60
	s_cselect_b32 s49, s25, s47
	s_cselect_b32 s48, s74, s46
	s_cselect_b32 s47, s23, s77
	s_cselect_b32 s46, s75, s76
	v_lshl_add_u64 v[216:217], s[34:35], 0, v[136:137]
	s_add_i32 m0, s21, 0xc000
	ds_read_b128 v[182:185], v149
	ds_read_b128 v[186:189], v149 offset:1024
	ds_read_b128 v[192:195], v149 offset:2048
	ds_read_b128 v[196:199], v149 offset:3072
	ds_read_b128 v[200:203], v149 offset:4096
	ds_read_b128 v[204:207], v149 offset:5120
	ds_read_b128 v[208:211], v149 offset:6144
	ds_read_b128 v[212:215], v149 offset:7168
	global_load_lds_dwordx4 v[216:217], off
	v_lshl_add_u64 v[216:217], s[34:35], 0, v[138:139]
	s_add_i32 m0, s21, 0xe000
	s_nop 0
	global_load_lds_dwordx4 v[216:217], off
	s_waitcnt vmcnt(8)
	s_waitcnt lgkmcnt(0)
	s_barrier
	s_setprio 1
	s_waitcnt lgkmcnt(0)
	v_mfma_f32_16x16x32_bf16 v[124:127], v[150:153], v[182:185], v[124:127]
	v_mfma_f32_16x16x32_bf16 v[120:123], v[158:161], v[182:185], v[120:123]
	v_mfma_f32_16x16x32_bf16 v[116:119], v[150:153], v[192:195], v[116:119]
	v_mfma_f32_16x16x32_bf16 v[112:115], v[158:161], v[192:195], v[112:115]
	v_mfma_f32_16x16x32_bf16 v[100:103], v[150:153], v[200:203], v[100:103]
	v_mfma_f32_16x16x32_bf16 v[96:99], v[158:161], v[200:203], v[96:99]
	v_mfma_f32_16x16x32_bf16 v[84:87], v[150:153], v[208:211], v[84:87]
	v_mfma_f32_16x16x32_bf16 v[80:83], v[158:161], v[208:211], v[80:83]
	v_mfma_f32_16x16x32_bf16 v[124:127], v[154:157], v[186:189], v[124:127]
	v_mfma_f32_16x16x32_bf16 v[120:123], v[162:165], v[186:189], v[120:123]
	v_mfma_f32_16x16x32_bf16 v[116:119], v[154:157], v[196:199], v[116:119]
	v_mfma_f32_16x16x32_bf16 v[112:115], v[162:165], v[196:199], v[112:115]
	v_mfma_f32_16x16x32_bf16 v[100:103], v[154:157], v[204:207], v[100:103]
	v_mfma_f32_16x16x32_bf16 v[96:99], v[162:165], v[204:207], v[96:99]
	v_mfma_f32_16x16x32_bf16 v[84:87], v[154:157], v[212:215], v[84:87]
	v_mfma_f32_16x16x32_bf16 v[80:83], v[162:165], v[212:215], v[80:83]
	v_mfma_f32_16x16x32_bf16 v[108:111], v[166:169], v[182:185], v[108:111]
	v_mfma_f32_16x16x32_bf16 v[104:107], v[174:177], v[182:185], v[104:107]
	v_mfma_f32_16x16x32_bf16 v[92:95], v[166:169], v[192:195], v[92:95]
	v_mfma_f32_16x16x32_bf16 v[88:91], v[174:177], v[192:195], v[88:91]
	v_mfma_f32_16x16x32_bf16 v[76:79], v[166:169], v[200:203], v[76:79]
	v_mfma_f32_16x16x32_bf16 v[72:75], v[174:177], v[200:203], v[72:75]
	v_mfma_f32_16x16x32_bf16 v[68:71], v[166:169], v[208:211], v[68:71]
	v_mfma_f32_16x16x32_bf16 v[64:67], v[174:177], v[208:211], v[64:67]
	v_mfma_f32_16x16x32_bf16 v[108:111], v[170:173], v[186:189], v[108:111]
	v_mfma_f32_16x16x32_bf16 v[104:107], v[178:181], v[186:189], v[104:107]
	v_mfma_f32_16x16x32_bf16 v[92:95], v[170:173], v[196:199], v[92:95]
	v_mfma_f32_16x16x32_bf16 v[88:91], v[178:181], v[196:199], v[88:91]
	v_mfma_f32_16x16x32_bf16 v[76:79], v[170:173], v[204:207], v[76:79]
	v_mfma_f32_16x16x32_bf16 v[72:75], v[178:181], v[204:207], v[72:75]
	v_mfma_f32_16x16x32_bf16 v[68:71], v[170:173], v[212:215], v[68:71]
	v_mfma_f32_16x16x32_bf16 v[64:67], v[178:181], v[212:215], v[64:67]
	s_setprio 0
	s_barrier
	s_add_i32 s79, s70, s51
	v_lshl_add_u64 v[216:217], s[46:47], 0, v[132:133]
	s_mov_b32 m0, s79
	ds_read_b128 v[182:185], v149 offset:16384
	ds_read_b128 v[186:189], v149 offset:17408
	ds_read_b128 v[192:195], v149 offset:18432
	ds_read_b128 v[196:199], v149 offset:19456
	ds_read_b128 v[200:203], v149 offset:20480
	ds_read_b128 v[204:207], v149 offset:21504
	ds_read_b128 v[208:211], v149 offset:22528
	ds_read_b128 v[212:215], v149 offset:23552
	global_load_lds_dwordx4 v[216:217], off
	s_add_i32 m0, s79, 0x2000
	s_add_u32 s80, s46, 0x100000
	v_lshl_add_u64 v[218:219], s[46:47], 0, v[128:129]
	s_addc_u32 s81, s47, 0
	s_add_i32 s79, s71, s51
	global_load_lds_dwordx4 v[218:219], off
	v_lshl_add_u64 v[220:221], s[80:81], 0, v[132:133]
	s_mov_b32 m0, s79
	v_lshl_add_u64 v[222:223], s[48:49], 0, v[130:131]
	global_load_lds_dwordx4 v[220:221], off
	v_lshl_add_u64 v[220:221], s[80:81], 0, v[128:129]
	s_add_i32 m0, s79, 0x2000
	s_nop 0
	global_load_lds_dwordx4 v[220:221], off
	v_lshl_add_u64 v[220:221], s[48:49], 0, v[134:135]
	s_mov_b32 m0, s21
	s_nop 0
	global_load_lds_dwordx4 v[220:221], off
	s_mov_b32 m0, s62
	s_nop 0
	global_load_lds_dwordx4 v[222:223], off
	s_waitcnt vmcnt(8)
	s_waitcnt lgkmcnt(0)
	s_barrier
; #define PG8_STAGE(bufoff, gbase, voff) do { _Pragma("unroll") for (int _i = 0; _i < 2; ++_i) \
;         __builtin_amdgcn_global_load_lds((const unsigned*)((const char*)(gbase) + (voff)[_i]), (LAS unsigned*)(lds + (bufoff) + ldsw + _i * 8192), 16, 0, 0); } while (0)
; #define PG8_LDA(dst, b, h) do { _Pragma("unroll") for (int m = 0; m < 4; ++m) _Pragma("unroll") for (int k = 0; k < 2; ++k) dst[m][k] = *(const LAS bf16x8*)(lds + PG8_SA(b, h) + aoff + m * 2048 + k * 1024); } while (0)
; #define PG8_LDB(dst, b, h) do { _Pragma("unroll") for (int n = 0; n < 2; ++n) _Pragma("unroll") for (int k = 0; k < 2; ++k) dst[n][k] = *(const LAS bf16x8*)(lds + PG8_SB(b, h) + boff + n * 2048 + k * 1024); } while (0)
; #define PG8_MMA(ai, bj, At, Bt) do { __builtin_amdgcn_s_setprio(1); _Pragma("unroll") for (int m = 0; m < 4; ++m) _Pragma("unroll") for (int n = 0; n < 2; ++n) _Pragma("unroll") for (int k = 0; k < 2; ++k) \
;         acc[ai][bj][m][n] = __builtin_amdgcn_mfma_f32_16x16x32_bf16(Bt[n][k], At[m][k], acc[ai][bj][m][n], 0, 0, 0); __builtin_amdgcn_s_setprio(0); } while (0)
; #define PG8_WAIT_V(n) asm volatile("s_waitcnt vmcnt(" #n ")" ::: "memory")
; #define PG8_WAIT_L(n) asm volatile("s_waitcnt lgkmcnt(" #n ")" ::: "memory")
; #define PG8_BAR __builtin_amdgcn_s_barrier()
; #define PG8_SCHED __builtin_amdgcn_sched_barrier(0)
; template <class Epi, bool ALIGN_EPI = true, bool SP2 = true>
; DI void gemm_phase(LAS unsigned char* lds, const Gemm g, const StaticOrder& S, const Epi& E) {
;     ...
;             PG8_WAIT_V(8); PG8_WAIT_L(0); PG8_BAR; PG8_MMA(1, 0, At, B0); PG8_MMA(1, 1, At, B1); PG8_BAR; PG8_SCHED;
;             PG8_LDB(B0, 1, 0); PG8_LDB(B1, 1, 1); PG8_SCHED; PG8_LDA(At, 1, 0); PG8_STAGE(PG8_SA(0, 1), a2 + hstepA, voffA);
;             PG8_WAIT_V(8); PG8_WAIT_L(0); PG8_BAR; PG8_MMA(0, 0, At, B0); PG8_MMA(0, 1, At, B1); PG8_BAR; PG8_SCHED;
;             PG8_LDA(At, 1, 1); PG8_STAGE(PG8_SB(1, 0), b3, voffB); PG8_STAGE(PG8_SB(1, 1), b3 + hstepB, voffB); PG8_STAGE(PG8_SA(1, 0), a3, voffA);
	s_setprio 1
	s_waitcnt lgkmcnt(0)
	v_mfma_f32_16x16x32_bf16 v[60:63], v[150:153], v[182:185], v[60:63]
	v_mfma_f32_16x16x32_bf16 v[56:59], v[158:161], v[182:185], v[56:59]
	v_mfma_f32_16x16x32_bf16 v[52:55], v[150:153], v[192:195], v[52:55]
	v_mfma_f32_16x16x32_bf16 v[48:51], v[158:161], v[192:195], v[48:51]
	v_mfma_f32_16x16x32_bf16 v[36:39], v[150:153], v[200:203], v[36:39]
	v_mfma_f32_16x16x32_bf16 v[32:35], v[158:161], v[200:203], v[32:35]
	v_mfma_f32_16x16x32_bf16 v[20:23], v[150:153], v[208:211], v[20:23]
	v_mfma_f32_16x16x32_bf16 v[16:19], v[158:161], v[208:211], v[16:19]
	v_mfma_f32_16x16x32_bf16 v[60:63], v[154:157], v[186:189], v[60:63]
	v_mfma_f32_16x16x32_bf16 v[56:59], v[162:165], v[186:189], v[56:59]
	v_mfma_f32_16x16x32_bf16 v[52:55], v[154:157], v[196:199], v[52:55]
	v_mfma_f32_16x16x32_bf16 v[48:51], v[162:165], v[196:199], v[48:51]
	v_mfma_f32_16x16x32_bf16 v[36:39], v[154:157], v[204:207], v[36:39]
	v_mfma_f32_16x16x32_bf16 v[32:35], v[162:165], v[204:207], v[32:35]
	v_mfma_f32_16x16x32_bf16 v[20:23], v[154:157], v[212:215], v[20:23]
	v_mfma_f32_16x16x32_bf16 v[16:19], v[162:165], v[212:215], v[16:19]
	v_mfma_f32_16x16x32_bf16 v[44:47], v[166:169], v[182:185], v[44:47]
	v_mfma_f32_16x16x32_bf16 v[40:43], v[174:177], v[182:185], v[40:43]
	v_mfma_f32_16x16x32_bf16 v[28:31], v[166:169], v[192:195], v[28:31]
	v_mfma_f32_16x16x32_bf16 v[24:27], v[174:177], v[192:195], v[24:27]
	v_mfma_f32_16x16x32_bf16 v[12:15], v[166:169], v[200:203], v[12:15]
	v_mfma_f32_16x16x32_bf16 v[8:11], v[174:177], v[200:203], v[8:11]
	v_mfma_f32_16x16x32_bf16 v[4:7], v[166:169], v[208:211], v[4:7]
	v_mfma_f32_16x16x32_bf16 v[0:3], v[174:177], v[208:211], v[0:3]
	v_mfma_f32_16x16x32_bf16 v[44:47], v[170:173], v[186:189], v[44:47]
	v_mfma_f32_16x16x32_bf16 v[40:43], v[178:181], v[186:189], v[40:43]
	v_mfma_f32_16x16x32_bf16 v[28:31], v[170:173], v[196:199], v[28:31]
	v_mfma_f32_16x16x32_bf16 v[24:27], v[178:181], v[196:199], v[24:27]
	v_mfma_f32_16x16x32_bf16 v[12:15], v[170:173], v[204:207], v[12:15]
	v_mfma_f32_16x16x32_bf16 v[8:11], v[178:181], v[204:207], v[8:11]
	v_mfma_f32_16x16x32_bf16 v[4:7], v[170:173], v[212:215], v[4:7]
	v_mfma_f32_16x16x32_bf16 v[0:3], v[178:181], v[212:215], v[0:3]
	s_setprio 0
	s_barrier
	s_add_i32 s79, 0, 0x18000
	s_add_i32 s80, 0, 0x1c000
	v_add_u32_e32 v162, s79, v145
	v_add_u32_e32 v178, s80, v145
	ds_read_b128 v[150:153], v162
	ds_read_b128 v[154:157], v162 offset:1024
	ds_read_b128 v[158:161], v162 offset:2048
	ds_read_b128 v[162:165], v162 offset:3072
	ds_read_b128 v[166:169], v178
	ds_read_b128 v[170:173], v178 offset:1024
	ds_read_b128 v[174:177], v178 offset:2048
	ds_read_b128 v[178:181], v178 offset:3072
	s_add_u32 s48, s48, 0x100000
	s_addc_u32 s49, s49, 0
	s_mov_b32 m0, s63
	v_lshl_add_u64 v[226:227], s[48:49], 0, v[134:135]
	ds_read_b128 v[182:185], v149 offset:32768
	ds_read_b128 v[186:189], v149 offset:33792
	ds_read_b128 v[192:195], v149 offset:34816
	ds_read_b128 v[196:199], v149 offset:35840
	ds_read_b128 v[200:203], v149 offset:36864
	ds_read_b128 v[204:207], v149 offset:37888
	ds_read_b128 v[208:211], v149 offset:38912
	ds_read_b128 v[212:215], v149 offset:39936
	global_load_lds_dwordx4 v[226:227], off
	v_lshl_add_u64 v[226:227], s[48:49], 0, v[130:131]
	s_mov_b32 m0, s64
	s_nop 0
	global_load_lds_dwordx4 v[226:227], off
	s_waitcnt vmcnt(8)
	s_waitcnt lgkmcnt(0)
	s_barrier
	s_setprio 1
	s_waitcnt lgkmcnt(0)
	v_mfma_f32_16x16x32_bf16 v[124:127], v[150:153], v[182:185], v[124:127]
	v_mfma_f32_16x16x32_bf16 v[120:123], v[158:161], v[182:185], v[120:123]
	v_mfma_f32_16x16x32_bf16 v[116:119], v[150:153], v[192:195], v[116:119]
	v_mfma_f32_16x16x32_bf16 v[112:115], v[158:161], v[192:195], v[112:115]
	v_mfma_f32_16x16x32_bf16 v[100:103], v[150:153], v[200:203], v[100:103]
	v_mfma_f32_16x16x32_bf16 v[96:99], v[158:161], v[200:203], v[96:99]
	v_mfma_f32_16x16x32_bf16 v[84:87], v[150:153], v[208:211], v[84:87]
	v_mfma_f32_16x16x32_bf16 v[80:83], v[158:161], v[208:211], v[80:83]
	v_mfma_f32_16x16x32_bf16 v[124:127], v[154:157], v[186:189], v[124:127]
	v_mfma_f32_16x16x32_bf16 v[120:123], v[162:165], v[186:189], v[120:123]
	v_mfma_f32_16x16x32_bf16 v[116:119], v[154:157], v[196:199], v[116:119]
	v_mfma_f32_16x16x32_bf16 v[112:115], v[162:165], v[196:199], v[112:115]
	v_mfma_f32_16x16x32_bf16 v[100:103], v[154:157], v[204:207], v[100:103]
	v_mfma_f32_16x16x32_bf16 v[96:99], v[162:165], v[204:207], v[96:99]
	v_mfma_f32_16x16x32_bf16 v[84:87], v[154:157], v[212:215], v[84:87]
	v_mfma_f32_16x16x32_bf16 v[80:83], v[162:165], v[212:215], v[80:83]
	v_mfma_f32_16x16x32_bf16 v[108:111], v[166:169], v[182:185], v[108:111]
	v_mfma_f32_16x16x32_bf16 v[104:107], v[174:177], v[182:185], v[104:107]
	v_mfma_f32_16x16x32_bf16 v[92:95], v[166:169], v[192:195], v[92:95]
	v_mfma_f32_16x16x32_bf16 v[88:91], v[174:177], v[192:195], v[88:91]
	v_mfma_f32_16x16x32_bf16 v[76:79], v[166:169], v[200:203], v[76:79]
	v_mfma_f32_16x16x32_bf16 v[72:75], v[174:177], v[200:203], v[72:75]
	v_mfma_f32_16x16x32_bf16 v[68:71], v[166:169], v[208:211], v[68:71]
	v_mfma_f32_16x16x32_bf16 v[64:67], v[174:177], v[208:211], v[64:67]
	v_mfma_f32_16x16x32_bf16 v[108:111], v[170:173], v[186:189], v[108:111]
	v_mfma_f32_16x16x32_bf16 v[104:107], v[178:181], v[186:189], v[104:107]
	v_mfma_f32_16x16x32_bf16 v[92:95], v[170:173], v[196:199], v[92:95]
	v_mfma_f32_16x16x32_bf16 v[88:91], v[178:181], v[196:199], v[88:91]
	v_mfma_f32_16x16x32_bf16 v[76:79], v[170:173], v[204:207], v[76:79]
	v_mfma_f32_16x16x32_bf16 v[72:75], v[178:181], v[204:207], v[72:75]
	v_mfma_f32_16x16x32_bf16 v[68:71], v[170:173], v[212:215], v[68:71]
	v_mfma_f32_16x16x32_bf16 v[64:67], v[178:181], v[212:215], v[64:67]
	s_setprio 0
	s_barrier
; #define PG8_STAGE(bufoff, gbase, voff) do { _Pragma("unroll") for (int _i = 0; _i < 2; ++_i) \
;         __builtin_amdgcn_global_load_lds((const unsigned*)((const char*)(gbase) + (voff)[_i]), (LAS unsigned*)(lds + (bufoff) + ldsw + _i * 8192), 16, 0, 0); } while (0)
; #define PG8_LDA(dst, b, h) do { _Pragma("unroll") for (int m = 0; m < 4; ++m) _Pragma("unroll") for (int k = 0; k < 2; ++k) dst[m][k] = *(const LAS bf16x8*)(lds + PG8_SA(b, h) + aoff + m * 2048 + k * 1024); } while (0)
; #define PG8_MMA(ai, bj, At, Bt) do { __builtin_amdgcn_s_setprio(1); _Pragma("unroll") for (int m = 0; m < 4; ++m) _Pragma("unroll") for (int n = 0; n < 2; ++n) _Pragma("unroll") for (int k = 0; k < 2; ++k) \
;         acc[ai][bj][m][n] = __builtin_amdgcn_mfma_f32_16x16x32_bf16(Bt[n][k], At[m][k], acc[ai][bj][m][n], 0, 0, 0); __builtin_amdgcn_s_setprio(0); } while (0)
; #define PG8_WAIT_V(n) asm volatile("s_waitcnt vmcnt(" #n ")" ::: "memory")
; #define PG8_WAIT_L(n) asm volatile("s_waitcnt lgkmcnt(" #n ")" ::: "memory")
; #define PG8_BAR __builtin_amdgcn_s_barrier()
; #define PG8_SCHED __builtin_amdgcn_sched_barrier(0)
; template <class Epi, bool ALIGN_EPI = true, bool SP2 = true>
; DI void gemm_phase(LAS unsigned char* lds, const Gemm g, const StaticOrder& S, const Epi& E) {
;     ...
;         for (int t = 0; t < nt; t += 2) {
;     ...
;             PG8_LDA(At, 1, 1); PG8_STAGE(PG8_SB(1, 0), b3, voffB); PG8_STAGE(PG8_SB(1, 1), b3 + hstepB, voffB); PG8_STAGE(PG8_SA(1, 0), a3, voffA);
;             PG8_WAIT_V(8); PG8_WAIT_L(0); PG8_BAR; PG8_MMA(1, 0, At, B0); PG8_MMA(1, 1, At, B1); PG8_BAR; PG8_SCHED;
	s_add_i32 s48, s79, s51
	v_lshl_add_u64 v[216:217], v[216:217], 0, s[10:11]
	s_mov_b32 m0, s48
	ds_read_b128 v[182:185], v149 offset:49152
	ds_read_b128 v[186:189], v149 offset:50176
	ds_read_b128 v[192:195], v149 offset:51200
	ds_read_b128 v[196:199], v149 offset:52224
	ds_read_b128 v[200:203], v149 offset:53248
	ds_read_b128 v[204:207], v149 offset:54272
	ds_read_b128 v[208:211], v149 offset:55296
	ds_read_b128 v[212:215], v149 offset:56320
	global_load_lds_dwordx4 v[216:217], off
	s_add_i32 m0, s48, 0x2000
	s_add_u32 s46, s46, 0x100080
	v_lshl_add_u64 v[216:217], v[218:219], 0, s[10:11]
	s_addc_u32 s47, s47, 0
	s_add_i32 s48, s80, s51
	global_load_lds_dwordx4 v[216:217], off
	v_lshl_add_u64 v[216:217], s[46:47], 0, v[132:133]
	s_mov_b32 m0, s48
	s_nop 0
	global_load_lds_dwordx4 v[216:217], off
	v_lshl_add_u64 v[216:217], s[46:47], 0, v[128:129]
	s_add_i32 m0, s48, 0x2000
	s_nop 0
	global_load_lds_dwordx4 v[216:217], off
	v_lshl_add_u64 v[216:217], v[220:221], 0, s[10:11]
	s_mov_b32 m0, s66
	s_nop 0
	global_load_lds_dwordx4 v[216:217], off
	v_lshl_add_u64 v[216:217], v[222:223], 0, s[10:11]
	s_mov_b32 m0, s67
	s_nop 0
	global_load_lds_dwordx4 v[216:217], off
	s_waitcnt vmcnt(8)
	s_waitcnt lgkmcnt(0)
	s_barrier
	s_setprio 1
	s_waitcnt lgkmcnt(0)
	v_mfma_f32_16x16x32_bf16 v[60:63], v[150:153], v[182:185], v[60:63]
	v_mfma_f32_16x16x32_bf16 v[56:59], v[158:161], v[182:185], v[56:59]
	v_mfma_f32_16x16x32_bf16 v[52:55], v[150:153], v[192:195], v[52:55]
	v_mfma_f32_16x16x32_bf16 v[48:51], v[158:161], v[192:195], v[48:51]
	v_mfma_f32_16x16x32_bf16 v[36:39], v[150:153], v[200:203], v[36:39]
	v_mfma_f32_16x16x32_bf16 v[32:35], v[158:161], v[200:203], v[32:35]
	v_mfma_f32_16x16x32_bf16 v[20:23], v[150:153], v[208:211], v[20:23]
	v_mfma_f32_16x16x32_bf16 v[16:19], v[158:161], v[208:211], v[16:19]
	v_mfma_f32_16x16x32_bf16 v[60:63], v[154:157], v[186:189], v[60:63]
	v_mfma_f32_16x16x32_bf16 v[56:59], v[162:165], v[186:189], v[56:59]
	v_mfma_f32_16x16x32_bf16 v[52:55], v[154:157], v[196:199], v[52:55]
	v_mfma_f32_16x16x32_bf16 v[48:51], v[162:165], v[196:199], v[48:51]
	v_mfma_f32_16x16x32_bf16 v[36:39], v[154:157], v[204:207], v[36:39]
	v_mfma_f32_16x16x32_bf16 v[32:35], v[162:165], v[204:207], v[32:35]
	v_mfma_f32_16x16x32_bf16 v[20:23], v[154:157], v[212:215], v[20:23]
	v_mfma_f32_16x16x32_bf16 v[16:19], v[162:165], v[212:215], v[16:19]
	v_mfma_f32_16x16x32_bf16 v[44:47], v[166:169], v[182:185], v[44:47]
	v_mfma_f32_16x16x32_bf16 v[40:43], v[174:177], v[182:185], v[40:43]
	v_mfma_f32_16x16x32_bf16 v[28:31], v[166:169], v[192:195], v[28:31]
	v_mfma_f32_16x16x32_bf16 v[24:27], v[174:177], v[192:195], v[24:27]
	v_mfma_f32_16x16x32_bf16 v[12:15], v[166:169], v[200:203], v[12:15]
	v_mfma_f32_16x16x32_bf16 v[8:11], v[174:177], v[200:203], v[8:11]
	v_mfma_f32_16x16x32_bf16 v[4:7], v[166:169], v[208:211], v[4:7]
	v_mfma_f32_16x16x32_bf16 v[0:3], v[174:177], v[208:211], v[0:3]
	v_mfma_f32_16x16x32_bf16 v[44:47], v[170:173], v[186:189], v[44:47]
	v_mfma_f32_16x16x32_bf16 v[40:43], v[178:181], v[186:189], v[40:43]
	v_mfma_f32_16x16x32_bf16 v[28:31], v[170:173], v[196:199], v[28:31]
	v_mfma_f32_16x16x32_bf16 v[24:27], v[178:181], v[196:199], v[24:27]
	v_mfma_f32_16x16x32_bf16 v[12:15], v[170:173], v[204:207], v[12:15]
	v_mfma_f32_16x16x32_bf16 v[8:11], v[178:181], v[204:207], v[8:11]
	v_mfma_f32_16x16x32_bf16 v[4:7], v[170:173], v[212:215], v[4:7]
	v_mfma_f32_16x16x32_bf16 v[0:3], v[178:181], v[212:215], v[0:3]
	s_setprio 0
	s_barrier
	s_add_i32 s78, s78, 2
	s_add_u32 s34, s34, 0x100
	s_addc_u32 s35, s35, 0
	s_add_u32 s76, s76, 0x100
	s_addc_u32 s77, s77, 0
	s_cmp_gt_u32 s78, 61
	s_cbranch_scc0 .LBB0_261
	s_and_b64 vcc, exec, s[18:19]
	s_cbranch_vccz .LBB0_264
	s_barrier

; #define PG8_STAGE(bufoff, gbase, voff) do { _Pragma("unroll") for (int _i = 0; _i < 2; ++_i) \
;         __builtin_amdgcn_global_load_lds((const unsigned*)((const char*)(gbase) + (voff)[_i]), (LAS unsigned*)(lds + (bufoff) + ldsw + _i * 8192), 16, 0, 0); } while (0)
; #define PG8_LDA(dst, b, h) do { _Pragma("unroll") for (int m = 0; m < 4; ++m) _Pragma("unroll") for (int k = 0; k < 2; ++k) dst[m][k] = *(const LAS bf16x8*)(lds + PG8_SA(b, h) + aoff + m * 2048 + k * 1024); } while (0)
; #define PG8_LDB(dst, b, h) do { _Pragma("unroll") for (int n = 0; n < 2; ++n) _Pragma("unroll") for (int k = 0; k < 2; ++k) dst[n][k] = *(const LAS bf16x8*)(lds + PG8_SB(b, h) + boff + n * 2048 + k * 1024); } while (0)
; #define PG8_MMA(ai, bj, At, Bt) do { __builtin_amdgcn_s_setprio(1); _Pragma("unroll") for (int m = 0; m < 4; ++m) _Pragma("unroll") for (int n = 0; n < 2; ++n) _Pragma("unroll") for (int k = 0; k < 2; ++k) \
;         acc[ai][bj][m][n] = __builtin_amdgcn_mfma_f32_16x16x32_bf16(Bt[n][k], At[m][k], acc[ai][bj][m][n], 0, 0, 0); __builtin_amdgcn_s_setprio(0); } while (0)
; #define PG8_WAIT_V(n) asm volatile("s_waitcnt vmcnt(" #n ")" ::: "memory")
; #define PG8_WAIT_L(n) asm volatile("s_waitcnt lgkmcnt(" #n ")" ::: "memory")
; #define PG8_BAR __builtin_amdgcn_s_barrier()
; #define PG8_SCHED __builtin_amdgcn_sched_barrier(0)
; template <class Epi, bool ALIGN_EPI = true, bool SP2 = true>
; DI void gemm_phase(LAS unsigned char* lds, const Gemm g, const StaticOrder& S, const Epi& E) {
;     ...
;             PG8_LDB(B0, 0, 0); PG8_LDB(B1, 0, 1); PG8_SCHED; PG8_LDA(At, 0, 0); PG8_STAGE(PG8_SA(1, 1), a1 + hstepA, voffA);
;             PG8_WAIT_V(8); PG8_WAIT_L(0); PG8_BAR; PG8_MMA(0, 0, At, B0); PG8_MMA(0, 1, At, B1); PG8_BAR; PG8_SCHED;
;             PG8_LDA(At, 0, 1); PG8_STAGE(PG8_SB(0, 0), b2, voffB); PG8_STAGE(PG8_SB(0, 1), b2 + hstepB, voffB); PG8_STAGE(PG8_SA(0, 0), a2, voffA);
;             PG8_WAIT_V(8); PG8_WAIT_L(0); PG8_BAR; PG8_MMA(1, 0, At, B0); PG8_MMA(1, 1, At, B1); PG8_BAR; PG8_SCHED;
.LBB0_334:
	ds_read_b128 v[162:165], v158
	ds_read_b128 v[166:169], v158 offset:1024
	ds_read_b128 v[170:173], v158 offset:2048
	ds_read_b128 v[174:177], v158 offset:3072
	ds_read_b128 v[178:181], v159
	ds_read_b128 v[182:185], v159 offset:1024
	ds_read_b128 v[186:189], v159 offset:2048
	ds_read_b128 v[192:195], v159 offset:3072
	s_add_u32 s30, s0, 0xffb80080
	s_addc_u32 s31, s1, -1
	s_cmp_eq_u32 s76, 12
	s_cselect_b32 s35, s25, s31
	s_cselect_b32 s34, s24, s30
	s_cselect_b32 s31, s23, s75
	s_cselect_b32 s30, s73, s74
	v_lshl_add_u64 v[230:231], s[0:1], 0, v[136:137]
	s_add_i32 m0, s49, 0xc000
	ds_read_b128 v[196:199], v160
	ds_read_b128 v[200:203], v160 offset:1024
	ds_read_b128 v[204:207], v160 offset:2048
	ds_read_b128 v[208:211], v160 offset:3072
	ds_read_b128 v[212:215], v160 offset:4096
	ds_read_b128 v[216:219], v160 offset:5120
	ds_read_b128 v[220:223], v160 offset:6144
	ds_read_b128 v[226:229], v160 offset:7168
	global_load_lds_dwordx4 v[230:231], off
	v_lshl_add_u64 v[230:231], s[0:1], 0, v[138:139]
	s_add_i32 m0, s49, 0xe000
	s_nop 0
	global_load_lds_dwordx4 v[230:231], off
	s_waitcnt vmcnt(8)
	s_waitcnt lgkmcnt(0)
	s_barrier
	s_setprio 1
	s_waitcnt lgkmcnt(0)
	v_mfma_f32_16x16x32_bf16 v[124:127], v[162:165], v[196:199], v[124:127]
	v_mfma_f32_16x16x32_bf16 v[120:123], v[170:173], v[196:199], v[120:123]
	v_mfma_f32_16x16x32_bf16 v[116:119], v[162:165], v[204:207], v[116:119]
	v_mfma_f32_16x16x32_bf16 v[112:115], v[170:173], v[204:207], v[112:115]
	v_mfma_f32_16x16x32_bf16 v[100:103], v[162:165], v[212:215], v[100:103]
	v_mfma_f32_16x16x32_bf16 v[96:99], v[170:173], v[212:215], v[96:99]
	v_mfma_f32_16x16x32_bf16 v[84:87], v[162:165], v[220:223], v[84:87]
	v_mfma_f32_16x16x32_bf16 v[80:83], v[170:173], v[220:223], v[80:83]
	v_mfma_f32_16x16x32_bf16 v[124:127], v[166:169], v[200:203], v[124:127]
	v_mfma_f32_16x16x32_bf16 v[120:123], v[174:177], v[200:203], v[120:123]
	v_mfma_f32_16x16x32_bf16 v[116:119], v[166:169], v[208:211], v[116:119]
	v_mfma_f32_16x16x32_bf16 v[112:115], v[174:177], v[208:211], v[112:115]
	v_mfma_f32_16x16x32_bf16 v[100:103], v[166:169], v[216:219], v[100:103]
	v_mfma_f32_16x16x32_bf16 v[96:99], v[174:177], v[216:219], v[96:99]
	v_mfma_f32_16x16x32_bf16 v[84:87], v[166:169], v[226:229], v[84:87]
	v_mfma_f32_16x16x32_bf16 v[80:83], v[174:177], v[226:229], v[80:83]
	v_mfma_f32_16x16x32_bf16 v[108:111], v[178:181], v[196:199], v[108:111]
	v_mfma_f32_16x16x32_bf16 v[104:107], v[186:189], v[196:199], v[104:107]
	v_mfma_f32_16x16x32_bf16 v[92:95], v[178:181], v[204:207], v[92:95]
	v_mfma_f32_16x16x32_bf16 v[88:91], v[186:189], v[204:207], v[88:91]
	v_mfma_f32_16x16x32_bf16 v[76:79], v[178:181], v[212:215], v[76:79]
	v_mfma_f32_16x16x32_bf16 v[72:75], v[186:189], v[212:215], v[72:75]
	v_mfma_f32_16x16x32_bf16 v[68:71], v[178:181], v[220:223], v[68:71]
	v_mfma_f32_16x16x32_bf16 v[64:67], v[186:189], v[220:223], v[64:67]
	v_mfma_f32_16x16x32_bf16 v[108:111], v[182:185], v[200:203], v[108:111]
	v_mfma_f32_16x16x32_bf16 v[104:107], v[192:195], v[200:203], v[104:107]
	v_mfma_f32_16x16x32_bf16 v[92:95], v[182:185], v[208:211], v[92:95]
	v_mfma_f32_16x16x32_bf16 v[88:91], v[192:195], v[208:211], v[88:91]
	v_mfma_f32_16x16x32_bf16 v[76:79], v[182:185], v[216:219], v[76:79]
	v_mfma_f32_16x16x32_bf16 v[72:75], v[192:195], v[216:219], v[72:75]
	v_mfma_f32_16x16x32_bf16 v[68:71], v[182:185], v[226:229], v[68:71]
	v_mfma_f32_16x16x32_bf16 v[64:67], v[192:195], v[226:229], v[64:67]
	s_setprio 0
	s_barrier
	s_add_i32 s77, s67, s47
	v_lshl_add_u64 v[230:231], s[30:31], 0, v[134:135]
	s_mov_b32 m0, s77
	ds_read_b128 v[196:199], v160 offset:16384
	ds_read_b128 v[200:203], v160 offset:17408
	ds_read_b128 v[204:207], v160 offset:18432
	ds_read_b128 v[208:211], v160 offset:19456
	ds_read_b128 v[212:215], v160 offset:20480
	ds_read_b128 v[216:219], v160 offset:21504
	ds_read_b128 v[220:223], v160 offset:22528
	ds_read_b128 v[226:229], v160 offset:23552
	global_load_lds_dwordx4 v[230:231], off
	s_add_i32 m0, s77, 0x2000
	s_add_u32 s78, s30, 0x40000
	v_lshl_add_u64 v[232:233], s[30:31], 0, v[132:133]
	s_addc_u32 s79, s31, 0
	s_add_i32 s77, s68, s47
	global_load_lds_dwordx4 v[232:233], off
	v_lshl_add_u64 v[234:235], s[78:79], 0, v[134:135]
	s_mov_b32 m0, s77
	v_lshl_add_u64 v[236:237], s[34:35], 0, v[130:131]
	global_load_lds_dwordx4 v[234:235], off
	v_lshl_add_u64 v[234:235], s[78:79], 0, v[132:133]
	s_add_i32 m0, s77, 0x2000
	s_nop 0
	global_load_lds_dwordx4 v[234:235], off
	v_lshl_add_u64 v[234:235], s[34:35], 0, v[128:129]
	s_mov_b32 m0, s49
	s_nop 0
	global_load_lds_dwordx4 v[234:235], off
	s_mov_b32 m0, s50
	s_nop 0
	global_load_lds_dwordx4 v[236:237], off
	s_waitcnt vmcnt(8)
	s_waitcnt lgkmcnt(0)
	s_barrier
; #define PG8_STAGE(bufoff, gbase, voff) do { _Pragma("unroll") for (int _i = 0; _i < 2; ++_i) \
;         __builtin_amdgcn_global_load_lds((const unsigned*)((const char*)(gbase) + (voff)[_i]), (LAS unsigned*)(lds + (bufoff) + ldsw + _i * 8192), 16, 0, 0); } while (0)
; #define PG8_LDA(dst, b, h) do { _Pragma("unroll") for (int m = 0; m < 4; ++m) _Pragma("unroll") for (int k = 0; k < 2; ++k) dst[m][k] = *(const LAS bf16x8*)(lds + PG8_SA(b, h) + aoff + m * 2048 + k * 1024); } while (0)
; #define PG8_LDB(dst, b, h) do { _Pragma("unroll") for (int n = 0; n < 2; ++n) _Pragma("unroll") for (int k = 0; k < 2; ++k) dst[n][k] = *(const LAS bf16x8*)(lds + PG8_SB(b, h) + boff + n * 2048 + k * 1024); } while (0)
; #define PG8_MMA(ai, bj, At, Bt) do { __builtin_amdgcn_s_setprio(1); _Pragma("unroll") for (int m = 0; m < 4; ++m) _Pragma("unroll") for (int n = 0; n < 2; ++n) _Pragma("unroll") for (int k = 0; k < 2; ++k) \
;         acc[ai][bj][m][n] = __builtin_amdgcn_mfma_f32_16x16x32_bf16(Bt[n][k], At[m][k], acc[ai][bj][m][n], 0, 0, 0); __builtin_amdgcn_s_setprio(0); } while (0)
; #define PG8_WAIT_V(n) asm volatile("s_waitcnt vmcnt(" #n ")" ::: "memory")
; #define PG8_WAIT_L(n) asm volatile("s_waitcnt lgkmcnt(" #n ")" ::: "memory")
; #define PG8_BAR __builtin_amdgcn_s_barrier()
; #define PG8_SCHED __builtin_amdgcn_sched_barrier(0)
; template <class Epi, bool ALIGN_EPI = true, bool SP2 = true>
; DI void gemm_phase(LAS unsigned char* lds, const Gemm g, const StaticOrder& S, const Epi& E) {
;     ...
;             PG8_WAIT_V(8); PG8_WAIT_L(0); PG8_BAR; PG8_MMA(1, 0, At, B0); PG8_MMA(1, 1, At, B1); PG8_BAR; PG8_SCHED;
;             PG8_LDB(B0, 1, 0); PG8_LDB(B1, 1, 1); PG8_SCHED; PG8_LDA(At, 1, 0); PG8_STAGE(PG8_SA(0, 1), a2 + hstepA, voffA);
;             PG8_WAIT_V(8); PG8_WAIT_L(0); PG8_BAR; PG8_MMA(0, 0, At, B0); PG8_MMA(0, 1, At, B1); PG8_BAR; PG8_SCHED;
;             PG8_LDA(At, 1, 1); PG8_STAGE(PG8_SB(1, 0), b3, voffB); PG8_STAGE(PG8_SB(1, 1), b3 + hstepB, voffB); PG8_STAGE(PG8_SA(1, 0), a3, voffA);
	s_setprio 1
	s_waitcnt lgkmcnt(0)
	v_mfma_f32_16x16x32_bf16 v[60:63], v[162:165], v[196:199], v[60:63]
	v_mfma_f32_16x16x32_bf16 v[56:59], v[170:173], v[196:199], v[56:59]
	v_mfma_f32_16x16x32_bf16 v[52:55], v[162:165], v[204:207], v[52:55]
	v_mfma_f32_16x16x32_bf16 v[48:51], v[170:173], v[204:207], v[48:51]
	v_mfma_f32_16x16x32_bf16 v[36:39], v[162:165], v[212:215], v[36:39]
	v_mfma_f32_16x16x32_bf16 v[32:35], v[170:173], v[212:215], v[32:35]
	v_mfma_f32_16x16x32_bf16 v[20:23], v[162:165], v[220:223], v[20:23]
	v_mfma_f32_16x16x32_bf16 v[16:19], v[170:173], v[220:223], v[16:19]
	v_mfma_f32_16x16x32_bf16 v[60:63], v[166:169], v[200:203], v[60:63]
	v_mfma_f32_16x16x32_bf16 v[56:59], v[174:177], v[200:203], v[56:59]
	v_mfma_f32_16x16x32_bf16 v[52:55], v[166:169], v[208:211], v[52:55]
	v_mfma_f32_16x16x32_bf16 v[48:51], v[174:177], v[208:211], v[48:51]
	v_mfma_f32_16x16x32_bf16 v[36:39], v[166:169], v[216:219], v[36:39]
	v_mfma_f32_16x16x32_bf16 v[32:35], v[174:177], v[216:219], v[32:35]
	v_mfma_f32_16x16x32_bf16 v[20:23], v[166:169], v[226:229], v[20:23]
	v_mfma_f32_16x16x32_bf16 v[16:19], v[174:177], v[226:229], v[16:19]
	v_mfma_f32_16x16x32_bf16 v[44:47], v[178:181], v[196:199], v[44:47]
	v_mfma_f32_16x16x32_bf16 v[40:43], v[186:189], v[196:199], v[40:43]
	v_mfma_f32_16x16x32_bf16 v[28:31], v[178:181], v[204:207], v[28:31]
	v_mfma_f32_16x16x32_bf16 v[24:27], v[186:189], v[204:207], v[24:27]
	v_mfma_f32_16x16x32_bf16 v[12:15], v[178:181], v[212:215], v[12:15]
	v_mfma_f32_16x16x32_bf16 v[8:11], v[186:189], v[212:215], v[8:11]
	v_mfma_f32_16x16x32_bf16 v[4:7], v[178:181], v[220:223], v[4:7]
	v_mfma_f32_16x16x32_bf16 v[0:3], v[186:189], v[220:223], v[0:3]
	v_mfma_f32_16x16x32_bf16 v[44:47], v[182:185], v[200:203], v[44:47]
	v_mfma_f32_16x16x32_bf16 v[40:43], v[192:195], v[200:203], v[40:43]
	v_mfma_f32_16x16x32_bf16 v[28:31], v[182:185], v[208:211], v[28:31]
	v_mfma_f32_16x16x32_bf16 v[24:27], v[192:195], v[208:211], v[24:27]
	v_mfma_f32_16x16x32_bf16 v[12:15], v[182:185], v[216:219], v[12:15]
	v_mfma_f32_16x16x32_bf16 v[8:11], v[192:195], v[216:219], v[8:11]
	v_mfma_f32_16x16x32_bf16 v[4:7], v[182:185], v[226:229], v[4:7]
	v_mfma_f32_16x16x32_bf16 v[0:3], v[192:195], v[226:229], v[0:3]
	s_setprio 0
	s_barrier
	s_add_i32 s77, 0, 0x18000
	v_add_u32_e32 v161, s77, v156
	s_add_i32 s78, 0, 0x1c000
	ds_read_b128 v[162:165], v161
	ds_read_b128 v[166:169], v161 offset:1024
	ds_read_b128 v[170:173], v161 offset:2048
	ds_read_b128 v[174:177], v161 offset:3072
	v_add_u32_e32 v161, s78, v156
	ds_read_b128 v[178:181], v161
	ds_read_b128 v[182:185], v161 offset:1024
	ds_read_b128 v[186:189], v161 offset:2048
	ds_read_b128 v[192:195], v161 offset:3072
	s_add_u32 s34, s34, 0x480000
	s_addc_u32 s35, s35, 0
	s_mov_b32 m0, s51
	v_lshl_add_u64 v[238:239], s[34:35], 0, v[128:129]
	ds_read_b128 v[196:199], v160 offset:32768
	ds_read_b128 v[200:203], v160 offset:33792
	ds_read_b128 v[204:207], v160 offset:34816
	ds_read_b128 v[208:211], v160 offset:35840
	ds_read_b128 v[212:215], v160 offset:36864
	ds_read_b128 v[216:219], v160 offset:37888
	ds_read_b128 v[220:223], v160 offset:38912
	ds_read_b128 v[226:229], v160 offset:39936
	global_load_lds_dwordx4 v[238:239], off
	v_lshl_add_u64 v[238:239], s[34:35], 0, v[130:131]
	s_mov_b32 m0, s60
	s_nop 0
	global_load_lds_dwordx4 v[238:239], off
	s_waitcnt vmcnt(8)
	s_waitcnt lgkmcnt(0)
	s_barrier
	s_setprio 1
	s_waitcnt lgkmcnt(0)
	v_mfma_f32_16x16x32_bf16 v[124:127], v[162:165], v[196:199], v[124:127]
	v_mfma_f32_16x16x32_bf16 v[120:123], v[170:173], v[196:199], v[120:123]
	v_mfma_f32_16x16x32_bf16 v[116:119], v[162:165], v[204:207], v[116:119]
	v_mfma_f32_16x16x32_bf16 v[112:115], v[170:173], v[204:207], v[112:115]
	v_mfma_f32_16x16x32_bf16 v[100:103], v[162:165], v[212:215], v[100:103]
	v_mfma_f32_16x16x32_bf16 v[96:99], v[170:173], v[212:215], v[96:99]
	v_mfma_f32_16x16x32_bf16 v[84:87], v[162:165], v[220:223], v[84:87]
	v_mfma_f32_16x16x32_bf16 v[80:83], v[170:173], v[220:223], v[80:83]
	v_mfma_f32_16x16x32_bf16 v[124:127], v[166:169], v[200:203], v[124:127]
	v_mfma_f32_16x16x32_bf16 v[120:123], v[174:177], v[200:203], v[120:123]
	v_mfma_f32_16x16x32_bf16 v[116:119], v[166:169], v[208:211], v[116:119]
	v_mfma_f32_16x16x32_bf16 v[112:115], v[174:177], v[208:211], v[112:115]
	v_mfma_f32_16x16x32_bf16 v[100:103], v[166:169], v[216:219], v[100:103]
	v_mfma_f32_16x16x32_bf16 v[96:99], v[174:177], v[216:219], v[96:99]
	v_mfma_f32_16x16x32_bf16 v[84:87], v[166:169], v[226:229], v[84:87]
	v_mfma_f32_16x16x32_bf16 v[80:83], v[174:177], v[226:229], v[80:83]
	v_mfma_f32_16x16x32_bf16 v[108:111], v[178:181], v[196:199], v[108:111]
	v_mfma_f32_16x16x32_bf16 v[104:107], v[186:189], v[196:199], v[104:107]
	v_mfma_f32_16x16x32_bf16 v[92:95], v[178:181], v[204:207], v[92:95]
	v_mfma_f32_16x16x32_bf16 v[88:91], v[186:189], v[204:207], v[88:91]
	v_mfma_f32_16x16x32_bf16 v[76:79], v[178:181], v[212:215], v[76:79]
	v_mfma_f32_16x16x32_bf16 v[72:75], v[186:189], v[212:215], v[72:75]
	v_mfma_f32_16x16x32_bf16 v[68:71], v[178:181], v[220:223], v[68:71]
	v_mfma_f32_16x16x32_bf16 v[64:67], v[186:189], v[220:223], v[64:67]
	v_mfma_f32_16x16x32_bf16 v[108:111], v[182:185], v[200:203], v[108:111]
	v_mfma_f32_16x16x32_bf16 v[104:107], v[192:195], v[200:203], v[104:107]
	v_mfma_f32_16x16x32_bf16 v[92:95], v[182:185], v[208:211], v[92:95]
	v_mfma_f32_16x16x32_bf16 v[88:91], v[192:195], v[208:211], v[88:91]
	v_mfma_f32_16x16x32_bf16 v[76:79], v[182:185], v[216:219], v[76:79]
	v_mfma_f32_16x16x32_bf16 v[72:75], v[192:195], v[216:219], v[72:75]
	v_mfma_f32_16x16x32_bf16 v[68:71], v[182:185], v[226:229], v[68:71]
	v_mfma_f32_16x16x32_bf16 v[64:67], v[192:195], v[226:229], v[64:67]
	s_setprio 0
	s_barrier
; #define PG8_STAGE(bufoff, gbase, voff) do { _Pragma("unroll") for (int _i = 0; _i < 2; ++_i) \
;         __builtin_amdgcn_global_load_lds((const unsigned*)((const char*)(gbase) + (voff)[_i]), (LAS unsigned*)(lds + (bufoff) + ldsw + _i * 8192), 16, 0, 0); } while (0)
; #define PG8_LDA(dst, b, h) do { _Pragma("unroll") for (int m = 0; m < 4; ++m) _Pragma("unroll") for (int k = 0; k < 2; ++k) dst[m][k] = *(const LAS bf16x8*)(lds + PG8_SA(b, h) + aoff + m * 2048 + k * 1024); } while (0)
; #define PG8_MMA(ai, bj, At, Bt) do { __builtin_amdgcn_s_setprio(1); _Pragma("unroll") for (int m = 0; m < 4; ++m) _Pragma("unroll") for (int n = 0; n < 2; ++n) _Pragma("unroll") for (int k = 0; k < 2; ++k) \
;         acc[ai][bj][m][n] = __builtin_amdgcn_mfma_f32_16x16x32_bf16(Bt[n][k], At[m][k], acc[ai][bj][m][n], 0, 0, 0); __builtin_amdgcn_s_setprio(0); } while (0)
; #define PG8_WAIT_V(n) asm volatile("s_waitcnt vmcnt(" #n ")" ::: "memory")
; #define PG8_WAIT_L(n) asm volatile("s_waitcnt lgkmcnt(" #n ")" ::: "memory")
; #define PG8_BAR __builtin_amdgcn_s_barrier()
; #define PG8_SCHED __builtin_amdgcn_sched_barrier(0)
; template <class Epi, bool ALIGN_EPI = true, bool SP2 = true>
; DI void gemm_phase(LAS unsigned char* lds, const Gemm g, const StaticOrder& S, const Epi& E) {
;     ...
;         for (int t = 0; t < nt; t += 2) {
;     ...
;             PG8_LDA(At, 1, 1); PG8_STAGE(PG8_SB(1, 0), b3, voffB); PG8_STAGE(PG8_SB(1, 1), b3 + hstepB, voffB); PG8_STAGE(PG8_SA(1, 0), a3, voffA);
;             PG8_WAIT_V(8); PG8_WAIT_L(0); PG8_BAR; PG8_MMA(1, 0, At, B0); PG8_MMA(1, 1, At, B1); PG8_BAR; PG8_SCHED;
	s_add_i32 s34, s77, s47
	v_lshl_add_u64 v[230:231], v[230:231], 0, s[18:19]
	s_mov_b32 m0, s34
	ds_read_b128 v[196:199], v160 offset:49152
	ds_read_b128 v[200:203], v160 offset:50176
	ds_read_b128 v[204:207], v160 offset:51200
	ds_read_b128 v[208:211], v160 offset:52224
	ds_read_b128 v[212:215], v160 offset:53248
	ds_read_b128 v[216:219], v160 offset:54272
	ds_read_b128 v[220:223], v160 offset:55296
	ds_read_b128 v[226:229], v160 offset:56320
	global_load_lds_dwordx4 v[230:231], off
	s_add_i32 m0, s34, 0x2000
	s_add_u32 s30, s30, 0x40080
	v_lshl_add_u64 v[230:231], v[232:233], 0, s[18:19]
	s_addc_u32 s31, s31, 0
	s_add_i32 s34, s78, s47
	global_load_lds_dwordx4 v[230:231], off
	v_lshl_add_u64 v[230:231], s[30:31], 0, v[134:135]
	s_mov_b32 m0, s34
	s_nop 0
	global_load_lds_dwordx4 v[230:231], off
	v_lshl_add_u64 v[230:231], s[30:31], 0, v[132:133]
	s_add_i32 m0, s34, 0x2000
	s_nop 0
	global_load_lds_dwordx4 v[230:231], off
	v_lshl_add_u64 v[230:231], v[234:235], 0, s[18:19]
	s_mov_b32 m0, s62
	s_nop 0
	global_load_lds_dwordx4 v[230:231], off
	v_lshl_add_u64 v[230:231], v[236:237], 0, s[18:19]
	s_mov_b32 m0, s63
	s_nop 0
	global_load_lds_dwordx4 v[230:231], off
	s_waitcnt vmcnt(8)
	s_waitcnt lgkmcnt(0)
	s_barrier
	s_setprio 1
	s_waitcnt lgkmcnt(0)
	v_mfma_f32_16x16x32_bf16 v[60:63], v[162:165], v[196:199], v[60:63]
	v_mfma_f32_16x16x32_bf16 v[56:59], v[170:173], v[196:199], v[56:59]
	v_mfma_f32_16x16x32_bf16 v[52:55], v[162:165], v[204:207], v[52:55]
	v_mfma_f32_16x16x32_bf16 v[48:51], v[170:173], v[204:207], v[48:51]
	v_mfma_f32_16x16x32_bf16 v[36:39], v[162:165], v[212:215], v[36:39]
	v_mfma_f32_16x16x32_bf16 v[32:35], v[170:173], v[212:215], v[32:35]
	v_mfma_f32_16x16x32_bf16 v[20:23], v[162:165], v[220:223], v[20:23]
	v_mfma_f32_16x16x32_bf16 v[16:19], v[170:173], v[220:223], v[16:19]
	v_mfma_f32_16x16x32_bf16 v[60:63], v[166:169], v[200:203], v[60:63]
	v_mfma_f32_16x16x32_bf16 v[56:59], v[174:177], v[200:203], v[56:59]
	v_mfma_f32_16x16x32_bf16 v[52:55], v[166:169], v[208:211], v[52:55]
	v_mfma_f32_16x16x32_bf16 v[48:51], v[174:177], v[208:211], v[48:51]
	v_mfma_f32_16x16x32_bf16 v[36:39], v[166:169], v[216:219], v[36:39]
	v_mfma_f32_16x16x32_bf16 v[32:35], v[174:177], v[216:219], v[32:35]
	v_mfma_f32_16x16x32_bf16 v[20:23], v[166:169], v[226:229], v[20:23]
	v_mfma_f32_16x16x32_bf16 v[16:19], v[174:177], v[226:229], v[16:19]
	v_mfma_f32_16x16x32_bf16 v[44:47], v[178:181], v[196:199], v[44:47]
	v_mfma_f32_16x16x32_bf16 v[40:43], v[186:189], v[196:199], v[40:43]
	v_mfma_f32_16x16x32_bf16 v[28:31], v[178:181], v[204:207], v[28:31]
	v_mfma_f32_16x16x32_bf16 v[24:27], v[186:189], v[204:207], v[24:27]
	v_mfma_f32_16x16x32_bf16 v[12:15], v[178:181], v[212:215], v[12:15]
	v_mfma_f32_16x16x32_bf16 v[8:11], v[186:189], v[212:215], v[8:11]
	v_mfma_f32_16x16x32_bf16 v[4:7], v[178:181], v[220:223], v[4:7]
	v_mfma_f32_16x16x32_bf16 v[0:3], v[186:189], v[220:223], v[0:3]
	v_mfma_f32_16x16x32_bf16 v[44:47], v[182:185], v[200:203], v[44:47]
	v_mfma_f32_16x16x32_bf16 v[40:43], v[192:195], v[200:203], v[40:43]
	v_mfma_f32_16x16x32_bf16 v[28:31], v[182:185], v[208:211], v[28:31]
	v_mfma_f32_16x16x32_bf16 v[24:27], v[192:195], v[208:211], v[24:27]
	v_mfma_f32_16x16x32_bf16 v[12:15], v[182:185], v[216:219], v[12:15]
	v_mfma_f32_16x16x32_bf16 v[8:11], v[192:195], v[216:219], v[8:11]
	v_mfma_f32_16x16x32_bf16 v[4:7], v[182:185], v[226:229], v[4:7]
	v_mfma_f32_16x16x32_bf16 v[0:3], v[192:195], v[226:229], v[0:3]
	s_setprio 0
	s_barrier
	s_add_i32 s76, s76, 2
	s_add_u32 s0, s0, 0x100
	s_addc_u32 s1, s1, 0
	s_add_u32 s74, s74, 0x100
	s_addc_u32 s75, s75, 0
	s_cmp_gt_u32 s76, 13
	s_cbranch_scc0 .LBB0_334
	s_and_b64 vcc, exec, s[20:21]
	s_cbranch_vccz .LBB0_337
	s_barrier

; #define PG8_STAGE(bufoff, gbase, voff) do { _Pragma("unroll") for (int _i = 0; _i < 2; ++_i) \
;         __builtin_amdgcn_global_load_lds((const unsigned*)((const char*)(gbase) + (voff)[_i]), (LAS unsigned*)(lds + (bufoff) + ldsw + _i * 8192), 16, 0, 0); } while (0)
; #define PG8_LDA(dst, b, h) do { _Pragma("unroll") for (int m = 0; m < 4; ++m) _Pragma("unroll") for (int k = 0; k < 2; ++k) dst[m][k] = *(const LAS bf16x8*)(lds + PG8_SA(b, h) + aoff + m * 2048 + k * 1024); } while (0)
; #define PG8_LDB(dst, b, h) do { _Pragma("unroll") for (int n = 0; n < 2; ++n) _Pragma("unroll") for (int k = 0; k < 2; ++k) dst[n][k] = *(const LAS bf16x8*)(lds + PG8_SB(b, h) + boff + n * 2048 + k * 1024); } while (0)
; #define PG8_MMA(ai, bj, At, Bt) do { __builtin_amdgcn_s_setprio(1); _Pragma("unroll") for (int m = 0; m < 4; ++m) _Pragma("unroll") for (int n = 0; n < 2; ++n) _Pragma("unroll") for (int k = 0; k < 2; ++k) \
;         acc[ai][bj][m][n] = __builtin_amdgcn_mfma_f32_16x16x32_bf16(Bt[n][k], At[m][k], acc[ai][bj][m][n], 0, 0, 0); __builtin_amdgcn_s_setprio(0); } while (0)
; #define PG8_WAIT_V(n) asm volatile("s_waitcnt vmcnt(" #n ")" ::: "memory")
; #define PG8_WAIT_L(n) asm volatile("s_waitcnt lgkmcnt(" #n ")" ::: "memory")
; #define PG8_BAR __builtin_amdgcn_s_barrier()
; #define PG8_SCHED __builtin_amdgcn_sched_barrier(0)
; template <class Epi, bool ALIGN_EPI = true, bool SP2 = true>
; DI void gemm_phase(LAS unsigned char* lds, const Gemm g, const StaticOrder& S, const Epi& E) {
;     ...
;             PG8_LDB(B0, 0, 0); PG8_LDB(B1, 0, 1); PG8_SCHED; PG8_LDA(At, 0, 0); PG8_STAGE(PG8_SA(1, 1), a1 + hstepA, voffA);
;             PG8_WAIT_V(8); PG8_WAIT_L(0); PG8_BAR; PG8_MMA(0, 0, At, B0); PG8_MMA(0, 1, At, B1); PG8_BAR; PG8_SCHED;
;             PG8_LDA(At, 0, 1); PG8_STAGE(PG8_SB(0, 0), b2, voffB); PG8_STAGE(PG8_SB(0, 1), b2 + hstepB, voffB); PG8_STAGE(PG8_SA(0, 0), a2, voffA);
;             PG8_WAIT_V(8); PG8_WAIT_L(0); PG8_BAR; PG8_MMA(1, 0, At, B0); PG8_MMA(1, 1, At, B1); PG8_BAR; PG8_SCHED;
.LBB0_360:
	ds_read_b128 v[154:157], v144
	ds_read_b128 v[158:161], v144 offset:1024
	ds_read_b128 v[162:165], v144 offset:2048
	ds_read_b128 v[166:169], v144 offset:3072
	ds_read_b128 v[170:173], v145
	ds_read_b128 v[174:177], v145 offset:1024
	ds_read_b128 v[178:181], v145 offset:2048
	ds_read_b128 v[182:185], v145 offset:3072
	s_add_u32 s60, s0, 0xffb80080
	s_addc_u32 s61, s1, -1
	s_cmp_eq_u32 s90, 4
	s_cselect_b32 s63, s49, s61
	s_cselect_b32 s62, s48, s60
	s_cselect_b32 s61, s47, s89
	s_cselect_b32 s60, s87, s88
	v_lshl_add_u64 v[150:151], s[0:1], 0, v[136:137]
	s_add_i32 m0, s69, 0xc000
	ds_read_b128 v[186:189], v148
	ds_read_b128 v[192:195], v148 offset:1024
	ds_read_b128 v[196:199], v148 offset:2048
	ds_read_b128 v[200:203], v148 offset:3072
	ds_read_b128 v[204:207], v148 offset:4096
	ds_read_b128 v[208:211], v148 offset:5120
	ds_read_b128 v[212:215], v148 offset:6144
	ds_read_b128 v[216:219], v148 offset:7168
	global_load_lds_dwordx4 v[150:151], off
	v_lshl_add_u64 v[150:151], s[0:1], 0, v[138:139]
	s_add_i32 m0, s69, 0xe000
	s_nop 0
	global_load_lds_dwordx4 v[150:151], off
	s_waitcnt vmcnt(8)
	s_waitcnt lgkmcnt(0)
	s_barrier
	s_setprio 1
	s_waitcnt lgkmcnt(0)
	v_mfma_f32_16x16x32_bf16 v[124:127], v[154:157], v[186:189], v[124:127]
	v_mfma_f32_16x16x32_bf16 v[120:123], v[162:165], v[186:189], v[120:123]
	v_mfma_f32_16x16x32_bf16 v[116:119], v[154:157], v[196:199], v[116:119]
	v_mfma_f32_16x16x32_bf16 v[112:115], v[162:165], v[196:199], v[112:115]
	v_mfma_f32_16x16x32_bf16 v[100:103], v[154:157], v[204:207], v[100:103]
	v_mfma_f32_16x16x32_bf16 v[96:99], v[162:165], v[204:207], v[96:99]
	v_mfma_f32_16x16x32_bf16 v[84:87], v[154:157], v[212:215], v[84:87]
	v_mfma_f32_16x16x32_bf16 v[80:83], v[162:165], v[212:215], v[80:83]
	v_mfma_f32_16x16x32_bf16 v[124:127], v[158:161], v[192:195], v[124:127]
	v_mfma_f32_16x16x32_bf16 v[120:123], v[166:169], v[192:195], v[120:123]
	v_mfma_f32_16x16x32_bf16 v[116:119], v[158:161], v[200:203], v[116:119]
	v_mfma_f32_16x16x32_bf16 v[112:115], v[166:169], v[200:203], v[112:115]
	v_mfma_f32_16x16x32_bf16 v[100:103], v[158:161], v[208:211], v[100:103]
	v_mfma_f32_16x16x32_bf16 v[96:99], v[166:169], v[208:211], v[96:99]
	v_mfma_f32_16x16x32_bf16 v[84:87], v[158:161], v[216:219], v[84:87]
	v_mfma_f32_16x16x32_bf16 v[80:83], v[166:169], v[216:219], v[80:83]
	v_mfma_f32_16x16x32_bf16 v[108:111], v[170:173], v[186:189], v[108:111]
	v_mfma_f32_16x16x32_bf16 v[104:107], v[178:181], v[186:189], v[104:107]
	v_mfma_f32_16x16x32_bf16 v[92:95], v[170:173], v[196:199], v[92:95]
	v_mfma_f32_16x16x32_bf16 v[88:91], v[178:181], v[196:199], v[88:91]
	v_mfma_f32_16x16x32_bf16 v[76:79], v[170:173], v[204:207], v[76:79]
	v_mfma_f32_16x16x32_bf16 v[72:75], v[178:181], v[204:207], v[72:75]
	v_mfma_f32_16x16x32_bf16 v[68:71], v[170:173], v[212:215], v[68:71]
	v_mfma_f32_16x16x32_bf16 v[64:67], v[178:181], v[212:215], v[64:67]
	v_mfma_f32_16x16x32_bf16 v[108:111], v[174:177], v[192:195], v[108:111]
	v_mfma_f32_16x16x32_bf16 v[104:107], v[182:185], v[192:195], v[104:107]
	v_mfma_f32_16x16x32_bf16 v[92:95], v[174:177], v[200:203], v[92:95]
	v_mfma_f32_16x16x32_bf16 v[88:91], v[182:185], v[200:203], v[88:91]
	v_mfma_f32_16x16x32_bf16 v[76:79], v[174:177], v[208:211], v[76:79]
	v_mfma_f32_16x16x32_bf16 v[72:75], v[182:185], v[208:211], v[72:75]
	v_mfma_f32_16x16x32_bf16 v[68:71], v[174:177], v[216:219], v[68:71]
	v_mfma_f32_16x16x32_bf16 v[64:67], v[182:185], v[216:219], v[64:67]
	s_setprio 0
	s_barrier
	s_add_i32 s91, s78, s68
	v_lshl_add_u64 v[150:151], s[60:61], 0, v[132:133]
	s_mov_b32 m0, s91
	ds_read_b128 v[186:189], v148 offset:16384
	ds_read_b128 v[192:195], v148 offset:17408
	ds_read_b128 v[196:199], v148 offset:18432
	ds_read_b128 v[200:203], v148 offset:19456
	ds_read_b128 v[204:207], v148 offset:20480
	ds_read_b128 v[208:211], v148 offset:21504
	ds_read_b128 v[212:215], v148 offset:22528
	ds_read_b128 v[216:219], v148 offset:23552
	global_load_lds_dwordx4 v[150:151], off
	s_add_i32 m0, s91, 0x2000
	s_add_u32 s92, s60, 0x20000
	v_lshl_add_u64 v[220:221], s[60:61], 0, v[134:135]
	s_addc_u32 s93, s61, 0
	s_add_i32 s91, s79, s68
	global_load_lds_dwordx4 v[220:221], off
	v_lshl_add_u64 v[222:223], s[92:93], 0, v[132:133]
	s_mov_b32 m0, s91
	v_lshl_add_u64 v[226:227], s[62:63], 0, v[130:131]
	global_load_lds_dwordx4 v[222:223], off
	v_lshl_add_u64 v[222:223], s[92:93], 0, v[134:135]
	s_add_i32 m0, s91, 0x2000
	s_nop 0
	global_load_lds_dwordx4 v[222:223], off
	v_lshl_add_u64 v[222:223], s[62:63], 0, v[128:129]
	s_mov_b32 m0, s69
	s_nop 0
	global_load_lds_dwordx4 v[222:223], off
	s_mov_b32 m0, s70
	s_nop 0
	global_load_lds_dwordx4 v[226:227], off
	s_waitcnt vmcnt(8)
	s_waitcnt lgkmcnt(0)
	s_barrier
; #define PG8_STAGE(bufoff, gbase, voff) do { _Pragma("unroll") for (int _i = 0; _i < 2; ++_i) \
;         __builtin_amdgcn_global_load_lds((const unsigned*)((const char*)(gbase) + (voff)[_i]), (LAS unsigned*)(lds + (bufoff) + ldsw + _i * 8192), 16, 0, 0); } while (0)
; #define PG8_LDA(dst, b, h) do { _Pragma("unroll") for (int m = 0; m < 4; ++m) _Pragma("unroll") for (int k = 0; k < 2; ++k) dst[m][k] = *(const LAS bf16x8*)(lds + PG8_SA(b, h) + aoff + m * 2048 + k * 1024); } while (0)
; #define PG8_LDB(dst, b, h) do { _Pragma("unroll") for (int n = 0; n < 2; ++n) _Pragma("unroll") for (int k = 0; k < 2; ++k) dst[n][k] = *(const LAS bf16x8*)(lds + PG8_SB(b, h) + boff + n * 2048 + k * 1024); } while (0)
; #define PG8_MMA(ai, bj, At, Bt) do { __builtin_amdgcn_s_setprio(1); _Pragma("unroll") for (int m = 0; m < 4; ++m) _Pragma("unroll") for (int n = 0; n < 2; ++n) _Pragma("unroll") for (int k = 0; k < 2; ++k) \
;         acc[ai][bj][m][n] = __builtin_amdgcn_mfma_f32_16x16x32_bf16(Bt[n][k], At[m][k], acc[ai][bj][m][n], 0, 0, 0); __builtin_amdgcn_s_setprio(0); } while (0)
; #define PG8_WAIT_V(n) asm volatile("s_waitcnt vmcnt(" #n ")" ::: "memory")
; #define PG8_WAIT_L(n) asm volatile("s_waitcnt lgkmcnt(" #n ")" ::: "memory")
; #define PG8_BAR __builtin_amdgcn_s_barrier()
; #define PG8_SCHED __builtin_amdgcn_sched_barrier(0)
; template <class Epi, bool ALIGN_EPI = true, bool SP2 = true>
; DI void gemm_phase(LAS unsigned char* lds, const Gemm g, const StaticOrder& S, const Epi& E) {
;     ...
;             PG8_WAIT_V(8); PG8_WAIT_L(0); PG8_BAR; PG8_MMA(1, 0, At, B0); PG8_MMA(1, 1, At, B1); PG8_BAR; PG8_SCHED;
;             PG8_LDB(B0, 1, 0); PG8_LDB(B1, 1, 1); PG8_SCHED; PG8_LDA(At, 1, 0); PG8_STAGE(PG8_SA(0, 1), a2 + hstepA, voffA);
;             PG8_WAIT_V(8); PG8_WAIT_L(0); PG8_BAR; PG8_MMA(0, 0, At, B0); PG8_MMA(0, 1, At, B1); PG8_BAR; PG8_SCHED;
;             PG8_LDA(At, 1, 1); PG8_STAGE(PG8_SB(1, 0), b3, voffB); PG8_STAGE(PG8_SB(1, 1), b3 + hstepB, voffB); PG8_STAGE(PG8_SA(1, 0), a3, voffA);
	s_setprio 1
	s_waitcnt lgkmcnt(0)
	v_mfma_f32_16x16x32_bf16 v[60:63], v[154:157], v[186:189], v[60:63]
	v_mfma_f32_16x16x32_bf16 v[56:59], v[162:165], v[186:189], v[56:59]
	v_mfma_f32_16x16x32_bf16 v[52:55], v[154:157], v[196:199], v[52:55]
	v_mfma_f32_16x16x32_bf16 v[48:51], v[162:165], v[196:199], v[48:51]
	v_mfma_f32_16x16x32_bf16 v[36:39], v[154:157], v[204:207], v[36:39]
	v_mfma_f32_16x16x32_bf16 v[32:35], v[162:165], v[204:207], v[32:35]
	v_mfma_f32_16x16x32_bf16 v[20:23], v[154:157], v[212:215], v[20:23]
	v_mfma_f32_16x16x32_bf16 v[16:19], v[162:165], v[212:215], v[16:19]
	v_mfma_f32_16x16x32_bf16 v[60:63], v[158:161], v[192:195], v[60:63]
	v_mfma_f32_16x16x32_bf16 v[56:59], v[166:169], v[192:195], v[56:59]
	v_mfma_f32_16x16x32_bf16 v[52:55], v[158:161], v[200:203], v[52:55]
	v_mfma_f32_16x16x32_bf16 v[48:51], v[166:169], v[200:203], v[48:51]
	v_mfma_f32_16x16x32_bf16 v[36:39], v[158:161], v[208:211], v[36:39]
	v_mfma_f32_16x16x32_bf16 v[32:35], v[166:169], v[208:211], v[32:35]
	v_mfma_f32_16x16x32_bf16 v[20:23], v[158:161], v[216:219], v[20:23]
	v_mfma_f32_16x16x32_bf16 v[16:19], v[166:169], v[216:219], v[16:19]
	v_mfma_f32_16x16x32_bf16 v[44:47], v[170:173], v[186:189], v[44:47]
	v_mfma_f32_16x16x32_bf16 v[40:43], v[178:181], v[186:189], v[40:43]
	v_mfma_f32_16x16x32_bf16 v[28:31], v[170:173], v[196:199], v[28:31]
	v_mfma_f32_16x16x32_bf16 v[24:27], v[178:181], v[196:199], v[24:27]
	v_mfma_f32_16x16x32_bf16 v[12:15], v[170:173], v[204:207], v[12:15]
	v_mfma_f32_16x16x32_bf16 v[8:11], v[178:181], v[204:207], v[8:11]
	v_mfma_f32_16x16x32_bf16 v[4:7], v[170:173], v[212:215], v[4:7]
	v_mfma_f32_16x16x32_bf16 v[0:3], v[178:181], v[212:215], v[0:3]
	v_mfma_f32_16x16x32_bf16 v[44:47], v[174:177], v[192:195], v[44:47]
	v_mfma_f32_16x16x32_bf16 v[40:43], v[182:185], v[192:195], v[40:43]
	v_mfma_f32_16x16x32_bf16 v[28:31], v[174:177], v[200:203], v[28:31]
	v_mfma_f32_16x16x32_bf16 v[24:27], v[182:185], v[200:203], v[24:27]
	v_mfma_f32_16x16x32_bf16 v[12:15], v[174:177], v[208:211], v[12:15]
	v_mfma_f32_16x16x32_bf16 v[8:11], v[182:185], v[208:211], v[8:11]
	v_mfma_f32_16x16x32_bf16 v[4:7], v[174:177], v[216:219], v[4:7]
	v_mfma_f32_16x16x32_bf16 v[0:3], v[182:185], v[216:219], v[0:3]
	s_setprio 0
	s_barrier
	s_add_i32 s91, 0, 0x18000
	v_add_u32_e32 v149, s91, v147
	s_add_i32 s92, 0, 0x1c000
	ds_read_b128 v[154:157], v149
	ds_read_b128 v[158:161], v149 offset:1024
	ds_read_b128 v[162:165], v149 offset:2048
	ds_read_b128 v[166:169], v149 offset:3072
	v_add_u32_e32 v149, s92, v147
	ds_read_b128 v[170:173], v149
	ds_read_b128 v[174:177], v149 offset:1024
	ds_read_b128 v[178:181], v149 offset:2048
	ds_read_b128 v[182:185], v149 offset:3072
	s_add_u32 s62, s62, 0x480000
	s_addc_u32 s63, s63, 0
	s_mov_b32 m0, s71
	v_lshl_add_u64 v[228:229], s[62:63], 0, v[128:129]
	ds_read_b128 v[186:189], v148 offset:32768
	ds_read_b128 v[192:195], v148 offset:33792
	ds_read_b128 v[196:199], v148 offset:34816
	ds_read_b128 v[200:203], v148 offset:35840
	ds_read_b128 v[204:207], v148 offset:36864
	ds_read_b128 v[208:211], v148 offset:37888
	ds_read_b128 v[212:215], v148 offset:38912
	ds_read_b128 v[216:219], v148 offset:39936
	global_load_lds_dwordx4 v[228:229], off
	v_lshl_add_u64 v[228:229], s[62:63], 0, v[130:131]
	s_mov_b32 m0, s72
	s_nop 0
	global_load_lds_dwordx4 v[228:229], off
	s_waitcnt vmcnt(8)
	s_waitcnt lgkmcnt(0)
	s_barrier
	s_setprio 1
	s_waitcnt lgkmcnt(0)
	v_mfma_f32_16x16x32_bf16 v[124:127], v[154:157], v[186:189], v[124:127]
	v_mfma_f32_16x16x32_bf16 v[120:123], v[162:165], v[186:189], v[120:123]
	v_mfma_f32_16x16x32_bf16 v[116:119], v[154:157], v[196:199], v[116:119]
	v_mfma_f32_16x16x32_bf16 v[112:115], v[162:165], v[196:199], v[112:115]
	v_mfma_f32_16x16x32_bf16 v[100:103], v[154:157], v[204:207], v[100:103]
	v_mfma_f32_16x16x32_bf16 v[96:99], v[162:165], v[204:207], v[96:99]
	v_mfma_f32_16x16x32_bf16 v[84:87], v[154:157], v[212:215], v[84:87]
	v_mfma_f32_16x16x32_bf16 v[80:83], v[162:165], v[212:215], v[80:83]
	v_mfma_f32_16x16x32_bf16 v[124:127], v[158:161], v[192:195], v[124:127]
	v_mfma_f32_16x16x32_bf16 v[120:123], v[166:169], v[192:195], v[120:123]
	v_mfma_f32_16x16x32_bf16 v[116:119], v[158:161], v[200:203], v[116:119]
	v_mfma_f32_16x16x32_bf16 v[112:115], v[166:169], v[200:203], v[112:115]
	v_mfma_f32_16x16x32_bf16 v[100:103], v[158:161], v[208:211], v[100:103]
	v_mfma_f32_16x16x32_bf16 v[96:99], v[166:169], v[208:211], v[96:99]
	v_mfma_f32_16x16x32_bf16 v[84:87], v[158:161], v[216:219], v[84:87]
	v_mfma_f32_16x16x32_bf16 v[80:83], v[166:169], v[216:219], v[80:83]
	v_mfma_f32_16x16x32_bf16 v[108:111], v[170:173], v[186:189], v[108:111]
	v_mfma_f32_16x16x32_bf16 v[104:107], v[178:181], v[186:189], v[104:107]
	v_mfma_f32_16x16x32_bf16 v[92:95], v[170:173], v[196:199], v[92:95]
	v_mfma_f32_16x16x32_bf16 v[88:91], v[178:181], v[196:199], v[88:91]
	v_mfma_f32_16x16x32_bf16 v[76:79], v[170:173], v[204:207], v[76:79]
	v_mfma_f32_16x16x32_bf16 v[72:75], v[178:181], v[204:207], v[72:75]
	v_mfma_f32_16x16x32_bf16 v[68:71], v[170:173], v[212:215], v[68:71]
	v_mfma_f32_16x16x32_bf16 v[64:67], v[178:181], v[212:215], v[64:67]
	v_mfma_f32_16x16x32_bf16 v[108:111], v[174:177], v[192:195], v[108:111]
	v_mfma_f32_16x16x32_bf16 v[104:107], v[182:185], v[192:195], v[104:107]
	v_mfma_f32_16x16x32_bf16 v[92:95], v[174:177], v[200:203], v[92:95]
	v_mfma_f32_16x16x32_bf16 v[88:91], v[182:185], v[200:203], v[88:91]
	v_mfma_f32_16x16x32_bf16 v[76:79], v[174:177], v[208:211], v[76:79]
	v_mfma_f32_16x16x32_bf16 v[72:75], v[182:185], v[208:211], v[72:75]
	v_mfma_f32_16x16x32_bf16 v[68:71], v[174:177], v[216:219], v[68:71]
	v_mfma_f32_16x16x32_bf16 v[64:67], v[182:185], v[216:219], v[64:67]
	s_setprio 0
	s_barrier
; #define PG8_STAGE(bufoff, gbase, voff) do { _Pragma("unroll") for (int _i = 0; _i < 2; ++_i) \
;         __builtin_amdgcn_global_load_lds((const unsigned*)((const char*)(gbase) + (voff)[_i]), (LAS unsigned*)(lds + (bufoff) + ldsw + _i * 8192), 16, 0, 0); } while (0)
; #define PG8_LDA(dst, b, h) do { _Pragma("unroll") for (int m = 0; m < 4; ++m) _Pragma("unroll") for (int k = 0; k < 2; ++k) dst[m][k] = *(const LAS bf16x8*)(lds + PG8_SA(b, h) + aoff + m * 2048 + k * 1024); } while (0)
; #define PG8_MMA(ai, bj, At, Bt) do { __builtin_amdgcn_s_setprio(1); _Pragma("unroll") for (int m = 0; m < 4; ++m) _Pragma("unroll") for (int n = 0; n < 2; ++n) _Pragma("unroll") for (int k = 0; k < 2; ++k) \
;         acc[ai][bj][m][n] = __builtin_amdgcn_mfma_f32_16x16x32_bf16(Bt[n][k], At[m][k], acc[ai][bj][m][n], 0, 0, 0); __builtin_amdgcn_s_setprio(0); } while (0)
; #define PG8_WAIT_V(n) asm volatile("s_waitcnt vmcnt(" #n ")" ::: "memory")
; #define PG8_WAIT_L(n) asm volatile("s_waitcnt lgkmcnt(" #n ")" ::: "memory")
; #define PG8_BAR __builtin_amdgcn_s_barrier()
; #define PG8_SCHED __builtin_amdgcn_sched_barrier(0)
; template <class Epi, bool ALIGN_EPI = true, bool SP2 = true>
; DI void gemm_phase(LAS unsigned char* lds, const Gemm g, const StaticOrder& S, const Epi& E) {
;     ...
;         for (int t = 0; t < nt; t += 2) {
;     ...
;             PG8_LDA(At, 1, 1); PG8_STAGE(PG8_SB(1, 0), b3, voffB); PG8_STAGE(PG8_SB(1, 1), b3 + hstepB, voffB); PG8_STAGE(PG8_SA(1, 0), a3, voffA);
;             PG8_WAIT_V(8); PG8_WAIT_L(0); PG8_BAR; PG8_MMA(1, 0, At, B0); PG8_MMA(1, 1, At, B1); PG8_BAR; PG8_SCHED;
	s_add_i32 s62, s91, s68
	v_lshl_add_u64 v[150:151], v[150:151], 0, s[20:21]
	s_mov_b32 m0, s62
	ds_read_b128 v[186:189], v148 offset:49152
	ds_read_b128 v[192:195], v148 offset:50176
	ds_read_b128 v[196:199], v148 offset:51200
	ds_read_b128 v[200:203], v148 offset:52224
	ds_read_b128 v[204:207], v148 offset:53248
	ds_read_b128 v[208:211], v148 offset:54272
	ds_read_b128 v[212:215], v148 offset:55296
	ds_read_b128 v[216:219], v148 offset:56320
	global_load_lds_dwordx4 v[150:151], off
	s_add_i32 m0, s62, 0x2000
	s_add_u32 s60, s60, 0x20080
	v_lshl_add_u64 v[150:151], v[220:221], 0, s[20:21]
	s_addc_u32 s61, s61, 0
	s_add_i32 s62, s92, s68
	global_load_lds_dwordx4 v[150:151], off
	v_lshl_add_u64 v[150:151], s[60:61], 0, v[132:133]
	s_mov_b32 m0, s62
	s_nop 0
	global_load_lds_dwordx4 v[150:151], off
	v_lshl_add_u64 v[150:151], s[60:61], 0, v[134:135]
	s_add_i32 m0, s62, 0x2000
	s_nop 0
	global_load_lds_dwordx4 v[150:151], off
	v_lshl_add_u64 v[150:151], v[222:223], 0, s[20:21]
	s_mov_b32 m0, s74
	s_nop 0
	global_load_lds_dwordx4 v[150:151], off
	v_lshl_add_u64 v[150:151], v[226:227], 0, s[20:21]
	s_mov_b32 m0, s75
	s_nop 0
	global_load_lds_dwordx4 v[150:151], off
	s_waitcnt vmcnt(8)
	s_waitcnt lgkmcnt(0)
	s_barrier
	s_setprio 1
	s_waitcnt lgkmcnt(0)
	v_mfma_f32_16x16x32_bf16 v[60:63], v[154:157], v[186:189], v[60:63]
	v_mfma_f32_16x16x32_bf16 v[56:59], v[162:165], v[186:189], v[56:59]
	v_mfma_f32_16x16x32_bf16 v[52:55], v[154:157], v[196:199], v[52:55]
	v_mfma_f32_16x16x32_bf16 v[48:51], v[162:165], v[196:199], v[48:51]
	v_mfma_f32_16x16x32_bf16 v[36:39], v[154:157], v[204:207], v[36:39]
	v_mfma_f32_16x16x32_bf16 v[32:35], v[162:165], v[204:207], v[32:35]
	v_mfma_f32_16x16x32_bf16 v[20:23], v[154:157], v[212:215], v[20:23]
	v_mfma_f32_16x16x32_bf16 v[16:19], v[162:165], v[212:215], v[16:19]
	v_mfma_f32_16x16x32_bf16 v[60:63], v[158:161], v[192:195], v[60:63]
	v_mfma_f32_16x16x32_bf16 v[56:59], v[166:169], v[192:195], v[56:59]
	v_mfma_f32_16x16x32_bf16 v[52:55], v[158:161], v[200:203], v[52:55]
	v_mfma_f32_16x16x32_bf16 v[48:51], v[166:169], v[200:203], v[48:51]
	v_mfma_f32_16x16x32_bf16 v[36:39], v[158:161], v[208:211], v[36:39]
	v_mfma_f32_16x16x32_bf16 v[32:35], v[166:169], v[208:211], v[32:35]
	v_mfma_f32_16x16x32_bf16 v[20:23], v[158:161], v[216:219], v[20:23]
	v_mfma_f32_16x16x32_bf16 v[16:19], v[166:169], v[216:219], v[16:19]
	v_mfma_f32_16x16x32_bf16 v[44:47], v[170:173], v[186:189], v[44:47]
	v_mfma_f32_16x16x32_bf16 v[40:43], v[178:181], v[186:189], v[40:43]
	v_mfma_f32_16x16x32_bf16 v[28:31], v[170:173], v[196:199], v[28:31]
	v_mfma_f32_16x16x32_bf16 v[24:27], v[178:181], v[196:199], v[24:27]
	v_mfma_f32_16x16x32_bf16 v[12:15], v[170:173], v[204:207], v[12:15]
	v_mfma_f32_16x16x32_bf16 v[8:11], v[178:181], v[204:207], v[8:11]
	v_mfma_f32_16x16x32_bf16 v[4:7], v[170:173], v[212:215], v[4:7]
	v_mfma_f32_16x16x32_bf16 v[0:3], v[178:181], v[212:215], v[0:3]
	v_mfma_f32_16x16x32_bf16 v[44:47], v[174:177], v[192:195], v[44:47]
	v_mfma_f32_16x16x32_bf16 v[40:43], v[182:185], v[192:195], v[40:43]
	v_mfma_f32_16x16x32_bf16 v[28:31], v[174:177], v[200:203], v[28:31]
	v_mfma_f32_16x16x32_bf16 v[24:27], v[182:185], v[200:203], v[24:27]
	v_mfma_f32_16x16x32_bf16 v[12:15], v[174:177], v[208:211], v[12:15]
	v_mfma_f32_16x16x32_bf16 v[8:11], v[182:185], v[208:211], v[8:11]
	v_mfma_f32_16x16x32_bf16 v[4:7], v[174:177], v[216:219], v[4:7]
	v_mfma_f32_16x16x32_bf16 v[0:3], v[182:185], v[216:219], v[0:3]
	s_setprio 0
	s_barrier
	s_add_i32 s90, s90, 2
	s_add_u32 s0, s0, 0x100
	s_addc_u32 s1, s1, 0
	s_add_u32 s88, s88, 0x100
	s_addc_u32 s89, s89, 0
	s_cmp_gt_u32 s90, 5
	s_cbranch_scc0 .LBB0_360
	s_and_b64 vcc, exec, s[22:23]
	s_cbranch_vccz .LBB0_363
	s_barrier

; #define PG8_STAGE(bufoff, gbase, voff) do { _Pragma("unroll") for (int _i = 0; _i < 2; ++_i) \
;         __builtin_amdgcn_global_load_lds((const unsigned*)((const char*)(gbase) + (voff)[_i]), (LAS unsigned*)(lds + (bufoff) + ldsw + _i * 8192), 16, 0, 0); } while (0)
; #define PG8_LDA(dst, b, h) do { _Pragma("unroll") for (int m = 0; m < 4; ++m) _Pragma("unroll") for (int k = 0; k < 2; ++k) dst[m][k] = *(const LAS bf16x8*)(lds + PG8_SA(b, h) + aoff + m * 2048 + k * 1024); } while (0)
; #define PG8_LDB(dst, b, h) do { _Pragma("unroll") for (int n = 0; n < 2; ++n) _Pragma("unroll") for (int k = 0; k < 2; ++k) dst[n][k] = *(const LAS bf16x8*)(lds + PG8_SB(b, h) + boff + n * 2048 + k * 1024); } while (0)
; #define PG8_MMA(ai, bj, At, Bt) do { __builtin_amdgcn_s_setprio(1); _Pragma("unroll") for (int m = 0; m < 4; ++m) _Pragma("unroll") for (int n = 0; n < 2; ++n) _Pragma("unroll") for (int k = 0; k < 2; ++k) \
;         acc[ai][bj][m][n] = __builtin_amdgcn_mfma_f32_16x16x32_bf16(Bt[n][k], At[m][k], acc[ai][bj][m][n], 0, 0, 0); __builtin_amdgcn_s_setprio(0); } while (0)
; #define PG8_WAIT_V(n) asm volatile("s_waitcnt vmcnt(" #n ")" ::: "memory")
; #define PG8_WAIT_L(n) asm volatile("s_waitcnt lgkmcnt(" #n ")" ::: "memory")
; #define PG8_BAR __builtin_amdgcn_s_barrier()
; #define PG8_SCHED __builtin_amdgcn_sched_barrier(0)
; template <class Epi, bool ALIGN_EPI = true, bool SP2 = true>
; DI void gemm_phase(LAS unsigned char* lds, const Gemm g, const StaticOrder& S, const Epi& E) {
;     ...
;             PG8_LDB(B0, 0, 0); PG8_LDB(B1, 0, 1); PG8_SCHED; PG8_LDA(At, 0, 0); PG8_STAGE(PG8_SA(1, 1), a1 + hstepA, voffA);
;             PG8_WAIT_V(8); PG8_WAIT_L(0); PG8_BAR; PG8_MMA(0, 0, At, B0); PG8_MMA(0, 1, At, B1); PG8_BAR; PG8_SCHED;
;             PG8_LDA(At, 0, 1); PG8_STAGE(PG8_SB(0, 0), b2, voffB); PG8_STAGE(PG8_SB(0, 1), b2 + hstepB, voffB); PG8_STAGE(PG8_SA(0, 0), a2, voffA);
;             PG8_WAIT_V(8); PG8_WAIT_L(0); PG8_BAR; PG8_MMA(1, 0, At, B0); PG8_MMA(1, 1, At, B1); PG8_BAR; PG8_SCHED;
.LBB0_755:
	v_add_u32_e32 v1, s67, v227
	ds_read_b128 v[132:135], v1
	ds_read_b128 v[136:139], v1 offset:1024
	ds_read_b128 v[140:143], v1 offset:2048
	ds_read_b128 v[144:147], v1 offset:3072
	v_add_u32_e32 v1, s68, v227
	s_add_u32 s8, s26, s30
	ds_read_b128 v[148:151], v1
	ds_read_b128 v[152:155], v1 offset:1024
	ds_read_b128 v[156:159], v1 offset:2048
	ds_read_b128 v[160:163], v1 offset:3072
	s_addc_u32 s9, s27, s31
	s_add_u32 s8, s8, 0x100
	s_addc_u32 s9, s9, 0
	s_add_u32 s34, s73, s30
	s_addc_u32 s35, s74, s31
	s_cmpk_eq_i32 s30, 0x1f00
	s_cselect_b32 s37, s21, s9
	s_cselect_b32 s36, s69, s8
	s_cselect_b32 s35, s70, s35
	s_cselect_b32 s34, s71, s34
	v_lshl_add_u64 v[2:3], v[188:189], 0, s[30:31]
	s_add_i32 m0, s43, 0xc000
	ds_read_b128 v[164:167], v229
	ds_read_b128 v[168:171], v229 offset:1024
	ds_read_b128 v[172:175], v229 offset:2048
	ds_read_b128 v[176:179], v229 offset:3072
	ds_read_b128 v[180:183], v229 offset:4096
	ds_read_b128 v[184:187], v229 offset:5120
	ds_read_b128 v[212:215], v229 offset:6144
	ds_read_b128 v[216:219], v229 offset:7168
	global_load_lds_dwordx4 v[2:3], off
	v_lshl_add_u64 v[2:3], v[190:191], 0, s[30:31]
	s_add_i32 m0, s43, 0xe000
	s_nop 0
	global_load_lds_dwordx4 v[2:3], off
	s_waitcnt vmcnt(8)
	s_waitcnt lgkmcnt(0)
	s_barrier
	s_setprio 1
	s_waitcnt lgkmcnt(0)
	v_mfma_f32_16x16x32_bf16 v[128:131], v[132:135], v[164:167], v[128:131]
	v_mfma_f32_16x16x32_bf16 v[124:127], v[140:143], v[164:167], v[124:127]
	v_mfma_f32_16x16x32_bf16 v[112:115], v[132:135], v[172:175], v[112:115]
	v_mfma_f32_16x16x32_bf16 v[108:111], v[140:143], v[172:175], v[108:111]
	v_mfma_f32_16x16x32_bf16 v[96:99], v[132:135], v[180:183], v[96:99]
	v_mfma_f32_16x16x32_bf16 v[92:95], v[140:143], v[180:183], v[92:95]
	v_mfma_f32_16x16x32_bf16 v[80:83], v[132:135], v[212:215], v[80:83]
	v_mfma_f32_16x16x32_bf16 v[76:79], v[140:143], v[212:215], v[76:79]
	v_mfma_f32_16x16x32_bf16 v[128:131], v[136:139], v[168:171], v[128:131]
	v_mfma_f32_16x16x32_bf16 v[124:127], v[144:147], v[168:171], v[124:127]
	v_mfma_f32_16x16x32_bf16 v[112:115], v[136:139], v[176:179], v[112:115]
	v_mfma_f32_16x16x32_bf16 v[108:111], v[144:147], v[176:179], v[108:111]
	v_mfma_f32_16x16x32_bf16 v[96:99], v[136:139], v[184:187], v[96:99]
	v_mfma_f32_16x16x32_bf16 v[92:95], v[144:147], v[184:187], v[92:95]
	v_mfma_f32_16x16x32_bf16 v[80:83], v[136:139], v[216:219], v[80:83]
	v_mfma_f32_16x16x32_bf16 v[76:79], v[144:147], v[216:219], v[76:79]
	v_mfma_f32_16x16x32_bf16 v[120:123], v[148:151], v[164:167], v[120:123]
	v_mfma_f32_16x16x32_bf16 v[116:119], v[156:159], v[164:167], v[116:119]
	v_mfma_f32_16x16x32_bf16 v[104:107], v[148:151], v[172:175], v[104:107]
	v_mfma_f32_16x16x32_bf16 v[100:103], v[156:159], v[172:175], v[100:103]
	v_mfma_f32_16x16x32_bf16 v[88:91], v[148:151], v[180:183], v[88:91]
	v_mfma_f32_16x16x32_bf16 v[84:87], v[156:159], v[180:183], v[84:87]
	v_mfma_f32_16x16x32_bf16 v[72:75], v[148:151], v[212:215], v[72:75]
	v_mfma_f32_16x16x32_bf16 v[68:71], v[156:159], v[212:215], v[68:71]
	v_mfma_f32_16x16x32_bf16 v[120:123], v[152:155], v[168:171], v[120:123]
	v_mfma_f32_16x16x32_bf16 v[116:119], v[160:163], v[168:171], v[116:119]
	v_mfma_f32_16x16x32_bf16 v[104:107], v[152:155], v[176:179], v[104:107]
	v_mfma_f32_16x16x32_bf16 v[100:103], v[160:163], v[176:179], v[100:103]
	v_mfma_f32_16x16x32_bf16 v[88:91], v[152:155], v[184:187], v[88:91]
	v_mfma_f32_16x16x32_bf16 v[84:87], v[160:163], v[184:187], v[84:87]
	v_mfma_f32_16x16x32_bf16 v[72:75], v[152:155], v[216:219], v[72:75]
	v_mfma_f32_16x16x32_bf16 v[68:71], v[160:163], v[216:219], v[68:71]
	s_setprio 0
	s_barrier
	s_add_i32 s8, s67, s42
	v_lshl_add_u64 v[220:221], s[34:35], 0, v[194:195]
	s_mov_b32 m0, s8
	ds_read_b128 v[164:167], v229 offset:16384
	ds_read_b128 v[168:171], v229 offset:17408
	ds_read_b128 v[172:175], v229 offset:18432
	ds_read_b128 v[176:179], v229 offset:19456
	ds_read_b128 v[180:183], v229 offset:20480
	ds_read_b128 v[184:187], v229 offset:21504
	ds_read_b128 v[212:215], v229 offset:22528
	ds_read_b128 v[216:219], v229 offset:23552
	global_load_lds_dwordx4 v[220:221], off
	s_add_i32 m0, s8, 0x2000
	s_add_u32 s76, s34, 0x100000
	v_lshl_add_u64 v[222:223], s[34:35], 0, v[198:199]
	s_addc_u32 s77, s35, 0
	s_add_i32 s8, s68, s42
	global_load_lds_dwordx4 v[222:223], off
	v_lshl_add_u64 v[2:3], s[76:77], 0, v[194:195]
	s_mov_b32 m0, s8
	v_lshl_add_u64 v[232:233], s[36:37], 0, v[192:193]
	global_load_lds_dwordx4 v[2:3], off
	v_lshl_add_u64 v[2:3], s[76:77], 0, v[198:199]
	s_add_i32 m0, s8, 0x2000
	v_lshl_add_u64 v[234:235], s[36:37], 0, v[196:197]
	global_load_lds_dwordx4 v[2:3], off
	s_mov_b32 m0, s43
	s_nop 0
	global_load_lds_dwordx4 v[232:233], off
	s_mov_b32 m0, s44
	s_nop 0
	global_load_lds_dwordx4 v[234:235], off
	s_waitcnt vmcnt(8)
	s_waitcnt lgkmcnt(0)
	s_barrier
; #define PG8_STAGE(bufoff, gbase, voff) do { _Pragma("unroll") for (int _i = 0; _i < 2; ++_i) \
;         __builtin_amdgcn_global_load_lds((const unsigned*)((const char*)(gbase) + (voff)[_i]), (LAS unsigned*)(lds + (bufoff) + ldsw + _i * 8192), 16, 0, 0); } while (0)
; #define PG8_LDA(dst, b, h) do { _Pragma("unroll") for (int m = 0; m < 4; ++m) _Pragma("unroll") for (int k = 0; k < 2; ++k) dst[m][k] = *(const LAS bf16x8*)(lds + PG8_SA(b, h) + aoff + m * 2048 + k * 1024); } while (0)
; #define PG8_LDB(dst, b, h) do { _Pragma("unroll") for (int n = 0; n < 2; ++n) _Pragma("unroll") for (int k = 0; k < 2; ++k) dst[n][k] = *(const LAS bf16x8*)(lds + PG8_SB(b, h) + boff + n * 2048 + k * 1024); } while (0)
; #define PG8_MMA(ai, bj, At, Bt) do { __builtin_amdgcn_s_setprio(1); _Pragma("unroll") for (int m = 0; m < 4; ++m) _Pragma("unroll") for (int n = 0; n < 2; ++n) _Pragma("unroll") for (int k = 0; k < 2; ++k) \
;         acc[ai][bj][m][n] = __builtin_amdgcn_mfma_f32_16x16x32_bf16(Bt[n][k], At[m][k], acc[ai][bj][m][n], 0, 0, 0); __builtin_amdgcn_s_setprio(0); } while (0)
; #define PG8_WAIT_V(n) asm volatile("s_waitcnt vmcnt(" #n ")" ::: "memory")
; #define PG8_WAIT_L(n) asm volatile("s_waitcnt lgkmcnt(" #n ")" ::: "memory")
; #define PG8_BAR __builtin_amdgcn_s_barrier()
; #define PG8_SCHED __builtin_amdgcn_sched_barrier(0)
; template <class Epi, bool ALIGN_EPI = true, bool SP2 = true>
; DI void gemm_phase(LAS unsigned char* lds, const Gemm g, const StaticOrder& S, const Epi& E) {
;     ...
;             PG8_WAIT_V(8); PG8_WAIT_L(0); PG8_BAR; PG8_MMA(1, 0, At, B0); PG8_MMA(1, 1, At, B1); PG8_BAR; PG8_SCHED;
;             PG8_LDB(B0, 1, 0); PG8_LDB(B1, 1, 1); PG8_SCHED; PG8_LDA(At, 1, 0); PG8_STAGE(PG8_SA(0, 1), a2 + hstepA, voffA);
;             PG8_WAIT_V(8); PG8_WAIT_L(0); PG8_BAR; PG8_MMA(0, 0, At, B0); PG8_MMA(0, 1, At, B1); PG8_BAR; PG8_SCHED;
;             PG8_LDA(At, 1, 1); PG8_STAGE(PG8_SB(1, 0), b3, voffB); PG8_STAGE(PG8_SB(1, 1), b3 + hstepB, voffB); PG8_STAGE(PG8_SA(1, 0), a3, voffA);
	s_setprio 1
	s_waitcnt lgkmcnt(0)
	v_mfma_f32_16x16x32_bf16 v[64:67], v[132:135], v[164:167], v[64:67]
	v_mfma_f32_16x16x32_bf16 v[60:63], v[140:143], v[164:167], v[60:63]
	v_mfma_f32_16x16x32_bf16 v[48:51], v[132:135], v[172:175], v[48:51]
	v_mfma_f32_16x16x32_bf16 v[44:47], v[140:143], v[172:175], v[44:47]
	v_mfma_f32_16x16x32_bf16 v[32:35], v[132:135], v[180:183], v[32:35]
	v_mfma_f32_16x16x32_bf16 v[28:31], v[140:143], v[180:183], v[28:31]
	v_mfma_f32_16x16x32_bf16 v[16:19], v[132:135], v[212:215], v[16:19]
	v_mfma_f32_16x16x32_bf16 v[12:15], v[140:143], v[212:215], v[12:15]
	v_mfma_f32_16x16x32_bf16 v[64:67], v[136:139], v[168:171], v[64:67]
	v_mfma_f32_16x16x32_bf16 v[60:63], v[144:147], v[168:171], v[60:63]
	v_mfma_f32_16x16x32_bf16 v[48:51], v[136:139], v[176:179], v[48:51]
	v_mfma_f32_16x16x32_bf16 v[44:47], v[144:147], v[176:179], v[44:47]
	v_mfma_f32_16x16x32_bf16 v[32:35], v[136:139], v[184:187], v[32:35]
	v_mfma_f32_16x16x32_bf16 v[28:31], v[144:147], v[184:187], v[28:31]
	v_mfma_f32_16x16x32_bf16 v[16:19], v[136:139], v[216:219], v[16:19]
	v_mfma_f32_16x16x32_bf16 v[12:15], v[144:147], v[216:219], v[12:15]
	v_mfma_f32_16x16x32_bf16 v[56:59], v[148:151], v[164:167], v[56:59]
	v_mfma_f32_16x16x32_bf16 v[52:55], v[156:159], v[164:167], v[52:55]
	v_mfma_f32_16x16x32_bf16 v[40:43], v[148:151], v[172:175], v[40:43]
	v_mfma_f32_16x16x32_bf16 v[36:39], v[156:159], v[172:175], v[36:39]
	v_mfma_f32_16x16x32_bf16 v[24:27], v[148:151], v[180:183], v[24:27]
	v_mfma_f32_16x16x32_bf16 v[20:23], v[156:159], v[180:183], v[20:23]
	v_mfma_f32_16x16x32_bf16 v[8:11], v[148:151], v[212:215], v[8:11]
	v_mfma_f32_16x16x32_bf16 v[2:5], v[156:159], v[212:215], v[4:7]
	v_mfma_f32_16x16x32_bf16 v[56:59], v[152:155], v[168:171], v[56:59]
	v_mfma_f32_16x16x32_bf16 v[52:55], v[160:163], v[168:171], v[52:55]
	v_mfma_f32_16x16x32_bf16 v[40:43], v[152:155], v[176:179], v[40:43]
	v_mfma_f32_16x16x32_bf16 v[36:39], v[160:163], v[176:179], v[36:39]
	v_mfma_f32_16x16x32_bf16 v[24:27], v[152:155], v[184:187], v[24:27]
	v_mfma_f32_16x16x32_bf16 v[20:23], v[160:163], v[184:187], v[20:23]
	v_mfma_f32_16x16x32_bf16 v[8:11], v[152:155], v[216:219], v[8:11]
	v_mfma_f32_16x16x32_bf16 v[2:5], v[160:163], v[216:219], v[2:5]
	s_setprio 0
	s_barrier
	s_add_i32 s8, 0, 0x18000
	v_add_u32_e32 v1, s8, v227
	s_add_i32 s9, 0, 0x1c000
	ds_read_b128 v[132:135], v1
	ds_read_b128 v[136:139], v1 offset:1024
	ds_read_b128 v[140:143], v1 offset:2048
	ds_read_b128 v[144:147], v1 offset:3072
	v_add_u32_e32 v1, s9, v227
	ds_read_b128 v[148:151], v1
	ds_read_b128 v[152:155], v1 offset:1024
	ds_read_b128 v[156:159], v1 offset:2048
	ds_read_b128 v[160:163], v1 offset:3072
	s_add_u32 s36, s36, 0x100000
	s_addc_u32 s37, s37, 0
	s_mov_b32 m0, s45
	v_lshl_add_u64 v[6:7], s[36:37], 0, v[192:193]
	ds_read_b128 v[164:167], v229 offset:32768
	ds_read_b128 v[168:171], v229 offset:33792
	ds_read_b128 v[172:175], v229 offset:34816
	ds_read_b128 v[176:179], v229 offset:35840
	ds_read_b128 v[180:183], v229 offset:36864
	ds_read_b128 v[184:187], v229 offset:37888
	ds_read_b128 v[212:215], v229 offset:38912
	ds_read_b128 v[216:219], v229 offset:39936
	global_load_lds_dwordx4 v[6:7], off
	v_lshl_add_u64 v[6:7], s[36:37], 0, v[196:197]
	s_mov_b32 m0, s46
	s_nop 0
	global_load_lds_dwordx4 v[6:7], off
	s_waitcnt vmcnt(8)
	s_waitcnt lgkmcnt(0)
	s_barrier
	s_setprio 1
	s_waitcnt lgkmcnt(0)
	v_mfma_f32_16x16x32_bf16 v[128:131], v[132:135], v[164:167], v[128:131]
	v_mfma_f32_16x16x32_bf16 v[124:127], v[140:143], v[164:167], v[124:127]
	v_mfma_f32_16x16x32_bf16 v[112:115], v[132:135], v[172:175], v[112:115]
	v_mfma_f32_16x16x32_bf16 v[108:111], v[140:143], v[172:175], v[108:111]
	v_mfma_f32_16x16x32_bf16 v[96:99], v[132:135], v[180:183], v[96:99]
	v_mfma_f32_16x16x32_bf16 v[92:95], v[140:143], v[180:183], v[92:95]
	v_mfma_f32_16x16x32_bf16 v[80:83], v[132:135], v[212:215], v[80:83]
	v_mfma_f32_16x16x32_bf16 v[76:79], v[140:143], v[212:215], v[76:79]
	v_mfma_f32_16x16x32_bf16 v[128:131], v[136:139], v[168:171], v[128:131]
	v_mfma_f32_16x16x32_bf16 v[124:127], v[144:147], v[168:171], v[124:127]
	v_mfma_f32_16x16x32_bf16 v[112:115], v[136:139], v[176:179], v[112:115]
	v_mfma_f32_16x16x32_bf16 v[108:111], v[144:147], v[176:179], v[108:111]
	v_mfma_f32_16x16x32_bf16 v[96:99], v[136:139], v[184:187], v[96:99]
	v_mfma_f32_16x16x32_bf16 v[92:95], v[144:147], v[184:187], v[92:95]
	v_mfma_f32_16x16x32_bf16 v[80:83], v[136:139], v[216:219], v[80:83]
	v_mfma_f32_16x16x32_bf16 v[76:79], v[144:147], v[216:219], v[76:79]
	v_mfma_f32_16x16x32_bf16 v[120:123], v[148:151], v[164:167], v[120:123]
	v_mfma_f32_16x16x32_bf16 v[116:119], v[156:159], v[164:167], v[116:119]
	v_mfma_f32_16x16x32_bf16 v[104:107], v[148:151], v[172:175], v[104:107]
	v_mfma_f32_16x16x32_bf16 v[100:103], v[156:159], v[172:175], v[100:103]
	v_mfma_f32_16x16x32_bf16 v[88:91], v[148:151], v[180:183], v[88:91]
	v_mfma_f32_16x16x32_bf16 v[84:87], v[156:159], v[180:183], v[84:87]
	v_mfma_f32_16x16x32_bf16 v[72:75], v[148:151], v[212:215], v[72:75]
	v_mfma_f32_16x16x32_bf16 v[68:71], v[156:159], v[212:215], v[68:71]
	v_mfma_f32_16x16x32_bf16 v[120:123], v[152:155], v[168:171], v[120:123]
	v_mfma_f32_16x16x32_bf16 v[116:119], v[160:163], v[168:171], v[116:119]
	v_mfma_f32_16x16x32_bf16 v[104:107], v[152:155], v[176:179], v[104:107]
	v_mfma_f32_16x16x32_bf16 v[100:103], v[160:163], v[176:179], v[100:103]
	v_mfma_f32_16x16x32_bf16 v[88:91], v[152:155], v[184:187], v[88:91]
	v_mfma_f32_16x16x32_bf16 v[84:87], v[160:163], v[184:187], v[84:87]
	v_mfma_f32_16x16x32_bf16 v[72:75], v[152:155], v[216:219], v[72:75]
	v_mfma_f32_16x16x32_bf16 v[68:71], v[160:163], v[216:219], v[68:71]
	s_setprio 0
	s_barrier
; #define PG8_STAGE(bufoff, gbase, voff) do { _Pragma("unroll") for (int _i = 0; _i < 2; ++_i) \
;         __builtin_amdgcn_global_load_lds((const unsigned*)((const char*)(gbase) + (voff)[_i]), (LAS unsigned*)(lds + (bufoff) + ldsw + _i * 8192), 16, 0, 0); } while (0)
; #define PG8_LDA(dst, b, h) do { _Pragma("unroll") for (int m = 0; m < 4; ++m) _Pragma("unroll") for (int k = 0; k < 2; ++k) dst[m][k] = *(const LAS bf16x8*)(lds + PG8_SA(b, h) + aoff + m * 2048 + k * 1024); } while (0)
; #define PG8_MMA(ai, bj, At, Bt) do { __builtin_amdgcn_s_setprio(1); _Pragma("unroll") for (int m = 0; m < 4; ++m) _Pragma("unroll") for (int n = 0; n < 2; ++n) _Pragma("unroll") for (int k = 0; k < 2; ++k) \
;         acc[ai][bj][m][n] = __builtin_amdgcn_mfma_f32_16x16x32_bf16(Bt[n][k], At[m][k], acc[ai][bj][m][n], 0, 0, 0); __builtin_amdgcn_s_setprio(0); } while (0)
; #define PG8_WAIT_V(n) asm volatile("s_waitcnt vmcnt(" #n ")" ::: "memory")
; #define PG8_WAIT_L(n) asm volatile("s_waitcnt lgkmcnt(" #n ")" ::: "memory")
; #define PG8_BAR __builtin_amdgcn_s_barrier()
; #define PG8_SCHED __builtin_amdgcn_sched_barrier(0)
; template <class Epi, bool ALIGN_EPI = true, bool SP2 = true>
; DI void gemm_phase(LAS unsigned char* lds, const Gemm g, const StaticOrder& S, const Epi& E) {
;     ...
;         for (int t = 0; t < nt; t += 2) {
;     ...
;             PG8_LDA(At, 1, 1); PG8_STAGE(PG8_SB(1, 0), b3, voffB); PG8_STAGE(PG8_SB(1, 1), b3 + hstepB, voffB); PG8_STAGE(PG8_SA(1, 0), a3, voffA);
;             PG8_WAIT_V(8); PG8_WAIT_L(0); PG8_BAR; PG8_MMA(1, 0, At, B0); PG8_MMA(1, 1, At, B1); PG8_BAR; PG8_SCHED;
	s_add_i32 s8, s8, s42
	v_lshl_add_u64 v[6:7], v[220:221], 0, s[10:11]
	s_mov_b32 m0, s8
	ds_read_b128 v[164:167], v229 offset:49152
	ds_read_b128 v[168:171], v229 offset:50176
	ds_read_b128 v[172:175], v229 offset:51200
	ds_read_b128 v[176:179], v229 offset:52224
	ds_read_b128 v[180:183], v229 offset:53248
	ds_read_b128 v[184:187], v229 offset:54272
	ds_read_b128 v[212:215], v229 offset:55296
	ds_read_b128 v[216:219], v229 offset:56320
	global_load_lds_dwordx4 v[6:7], off
	s_add_i32 m0, s8, 0x2000
	s_add_u32 s34, s34, 0x100080
	v_lshl_add_u64 v[6:7], v[222:223], 0, s[10:11]
	s_addc_u32 s35, s35, 0
	s_add_i32 s8, s9, s42
	global_load_lds_dwordx4 v[6:7], off
	v_lshl_add_u64 v[6:7], s[34:35], 0, v[194:195]
	s_mov_b32 m0, s8
	s_nop 0
	global_load_lds_dwordx4 v[6:7], off
	v_lshl_add_u64 v[6:7], s[34:35], 0, v[198:199]
	s_add_i32 m0, s8, 0x2000
	s_nop 0
	global_load_lds_dwordx4 v[6:7], off
	v_lshl_add_u64 v[6:7], v[232:233], 0, s[10:11]
	s_mov_b32 m0, s51
	s_nop 0
	global_load_lds_dwordx4 v[6:7], off
	v_lshl_add_u64 v[6:7], v[234:235], 0, s[10:11]
	s_mov_b32 m0, s60
	s_nop 0
	global_load_lds_dwordx4 v[6:7], off
	s_waitcnt vmcnt(8)
	s_waitcnt lgkmcnt(0)
	s_barrier
	s_setprio 1
	s_waitcnt lgkmcnt(0)
	v_mfma_f32_16x16x32_bf16 v[64:67], v[132:135], v[164:167], v[64:67]
	v_mfma_f32_16x16x32_bf16 v[60:63], v[140:143], v[164:167], v[60:63]
	v_mfma_f32_16x16x32_bf16 v[48:51], v[132:135], v[172:175], v[48:51]
	v_mfma_f32_16x16x32_bf16 v[44:47], v[140:143], v[172:175], v[44:47]
	v_mfma_f32_16x16x32_bf16 v[32:35], v[132:135], v[180:183], v[32:35]
	v_mfma_f32_16x16x32_bf16 v[28:31], v[140:143], v[180:183], v[28:31]
	v_mfma_f32_16x16x32_bf16 v[16:19], v[132:135], v[212:215], v[16:19]
	v_mfma_f32_16x16x32_bf16 v[12:15], v[140:143], v[212:215], v[12:15]
	v_mfma_f32_16x16x32_bf16 v[64:67], v[136:139], v[168:171], v[64:67]
	v_mfma_f32_16x16x32_bf16 v[60:63], v[144:147], v[168:171], v[60:63]
	v_mfma_f32_16x16x32_bf16 v[48:51], v[136:139], v[176:179], v[48:51]
	v_mfma_f32_16x16x32_bf16 v[44:47], v[144:147], v[176:179], v[44:47]
	v_mfma_f32_16x16x32_bf16 v[32:35], v[136:139], v[184:187], v[32:35]
	v_mfma_f32_16x16x32_bf16 v[28:31], v[144:147], v[184:187], v[28:31]
	v_mfma_f32_16x16x32_bf16 v[16:19], v[136:139], v[216:219], v[16:19]
	v_mfma_f32_16x16x32_bf16 v[12:15], v[144:147], v[216:219], v[12:15]
	v_mfma_f32_16x16x32_bf16 v[56:59], v[148:151], v[164:167], v[56:59]
	v_mfma_f32_16x16x32_bf16 v[52:55], v[156:159], v[164:167], v[52:55]
	v_mfma_f32_16x16x32_bf16 v[40:43], v[148:151], v[172:175], v[40:43]
	v_mfma_f32_16x16x32_bf16 v[36:39], v[156:159], v[172:175], v[36:39]
	v_mfma_f32_16x16x32_bf16 v[24:27], v[148:151], v[180:183], v[24:27]
	v_mfma_f32_16x16x32_bf16 v[20:23], v[156:159], v[180:183], v[20:23]
	v_mfma_f32_16x16x32_bf16 v[6:9], v[148:151], v[212:215], v[8:11]
	v_mfma_f32_16x16x32_bf16 v[2:5], v[156:159], v[212:215], v[2:5]
	v_mfma_f32_16x16x32_bf16 v[56:59], v[152:155], v[168:171], v[56:59]
	v_mfma_f32_16x16x32_bf16 v[52:55], v[160:163], v[168:171], v[52:55]
	v_mfma_f32_16x16x32_bf16 v[40:43], v[152:155], v[176:179], v[40:43]
	v_mfma_f32_16x16x32_bf16 v[36:39], v[160:163], v[176:179], v[36:39]
	v_mfma_f32_16x16x32_bf16 v[24:27], v[152:155], v[184:187], v[24:27]
	v_mfma_f32_16x16x32_bf16 v[20:23], v[160:163], v[184:187], v[20:23]
	v_mfma_f32_16x16x32_bf16 v[8:11], v[152:155], v[216:219], v[6:9]
	v_mfma_f32_16x16x32_bf16 v[4:7], v[160:163], v[216:219], v[2:5]
	s_setprio 0
	s_barrier
	s_add_i32 s75, s75, 2
	s_add_u32 s30, s30, 0x100
	s_addc_u32 s31, s31, 0
	s_cmp_gt_u32 s75, 61
	s_cbranch_scc1 .LBB0_761

; #define PG8_STAGE(bufoff, gbase, voff) do { _Pragma("unroll") for (int _i = 0; _i < 2; ++_i) \
;         __builtin_amdgcn_global_load_lds((const unsigned*)((const char*)(gbase) + (voff)[_i]), (LAS unsigned*)(lds + (bufoff) + ldsw + _i * 8192), 16, 0, 0); } while (0)
; #define PG8_LDA(dst, b, h) do { _Pragma("unroll") for (int m = 0; m < 4; ++m) _Pragma("unroll") for (int k = 0; k < 2; ++k) dst[m][k] = *(const LAS bf16x8*)(lds + PG8_SA(b, h) + aoff + m * 2048 + k * 1024); } while (0)
; #define PG8_LDB(dst, b, h) do { _Pragma("unroll") for (int n = 0; n < 2; ++n) _Pragma("unroll") for (int k = 0; k < 2; ++k) dst[n][k] = *(const LAS bf16x8*)(lds + PG8_SB(b, h) + boff + n * 2048 + k * 1024); } while (0)
; #define PG8_MMA(ai, bj, At, Bt) do { __builtin_amdgcn_s_setprio(1); _Pragma("unroll") for (int m = 0; m < 4; ++m) _Pragma("unroll") for (int n = 0; n < 2; ++n) _Pragma("unroll") for (int k = 0; k < 2; ++k) \
;         acc[ai][bj][m][n] = __builtin_amdgcn_mfma_f32_16x16x32_bf16(Bt[n][k], At[m][k], acc[ai][bj][m][n], 0, 0, 0); __builtin_amdgcn_s_setprio(0); } while (0)
; #define PG8_WAIT_V(n) asm volatile("s_waitcnt vmcnt(" #n ")" ::: "memory")
; #define PG8_WAIT_L(n) asm volatile("s_waitcnt lgkmcnt(" #n ")" ::: "memory")
; #define PG8_BAR __builtin_amdgcn_s_barrier()
; #define PG8_SCHED __builtin_amdgcn_sched_barrier(0)
; template <class Epi, bool ALIGN_EPI = true, bool SP2 = true>
; DI void gemm_phase(LAS unsigned char* lds, const Gemm g, const StaticOrder& S, const Epi& E) {
;     ...
;             PG8_LDB(B0, 0, 0); PG8_LDB(B1, 0, 1); PG8_SCHED; PG8_LDA(At, 0, 0); PG8_STAGE(PG8_SA(1, 1), a1 + hstepA, voffA);
;             PG8_WAIT_V(8); PG8_WAIT_L(0); PG8_BAR; PG8_MMA(0, 0, At, B0); PG8_MMA(0, 1, At, B1); PG8_BAR; PG8_SCHED;
;             PG8_LDA(At, 0, 1); PG8_STAGE(PG8_SB(0, 0), b2, voffB); PG8_STAGE(PG8_SB(0, 1), b2 + hstepB, voffB); PG8_STAGE(PG8_SA(0, 0), a2, voffA);
;             PG8_WAIT_V(8); PG8_WAIT_L(0); PG8_BAR; PG8_MMA(1, 0, At, B0); PG8_MMA(1, 1, At, B1); PG8_BAR; PG8_SCHED;
.LBB0_839:
	ds_read_b128 v[140:143], v149
	ds_read_b128 v[152:155], v149 offset:1024
	ds_read_b128 v[156:159], v149 offset:2048
	ds_read_b128 v[160:163], v149 offset:3072
	ds_read_b128 v[164:167], v150
	ds_read_b128 v[168:171], v150 offset:1024
	ds_read_b128 v[172:175], v150 offset:2048
	ds_read_b128 v[176:179], v150 offset:3072
	s_add_u32 s34, s30, 0xfff00080
	s_addc_u32 s35, s31, -1
	s_cmp_eq_u32 s59, 60
	s_cselect_b32 s37, s23, s35
	s_cselect_b32 s36, s50, s34
	s_cselect_b32 s35, s21, s57
	s_cselect_b32 s34, s51, s56
	v_lshl_add_u64 v[144:145], s[30:31], 0, v[132:133]
	s_add_i32 m0, s29, 0xc000
	ds_read_b128 v[180:183], v151
	ds_read_b128 v[184:187], v151 offset:1024
	ds_read_b128 v[188:191], v151 offset:2048
	ds_read_b128 v[192:195], v151 offset:3072
	ds_read_b128 v[196:199], v151 offset:4096
	ds_read_b128 v[200:203], v151 offset:5120
	ds_read_b128 v[204:207], v151 offset:6144
	ds_read_b128 v[208:211], v151 offset:7168
	global_load_lds_dwordx4 v[144:145], off
	v_lshl_add_u64 v[144:145], s[30:31], 0, v[134:135]
	s_add_i32 m0, s29, 0xe000
	s_nop 0
	global_load_lds_dwordx4 v[144:145], off
	s_waitcnt vmcnt(8)
	s_waitcnt lgkmcnt(0)
	s_barrier
	s_setprio 1
	s_waitcnt lgkmcnt(0)
	v_mfma_f32_16x16x32_bf16 v[124:127], v[140:143], v[180:183], v[124:127]
	v_mfma_f32_16x16x32_bf16 v[120:123], v[156:159], v[180:183], v[120:123]
	v_mfma_f32_16x16x32_bf16 v[116:119], v[140:143], v[188:191], v[116:119]
	v_mfma_f32_16x16x32_bf16 v[112:115], v[156:159], v[188:191], v[112:115]
	v_mfma_f32_16x16x32_bf16 v[108:111], v[140:143], v[196:199], v[108:111]
	v_mfma_f32_16x16x32_bf16 v[100:103], v[156:159], v[196:199], v[100:103]
	v_mfma_f32_16x16x32_bf16 v[92:95], v[140:143], v[204:207], v[92:95]
	v_mfma_f32_16x16x32_bf16 v[80:83], v[156:159], v[204:207], v[80:83]
	v_mfma_f32_16x16x32_bf16 v[124:127], v[152:155], v[184:187], v[124:127]
	v_mfma_f32_16x16x32_bf16 v[120:123], v[160:163], v[184:187], v[120:123]
	v_mfma_f32_16x16x32_bf16 v[116:119], v[152:155], v[192:195], v[116:119]
	v_mfma_f32_16x16x32_bf16 v[112:115], v[160:163], v[192:195], v[112:115]
	v_mfma_f32_16x16x32_bf16 v[108:111], v[152:155], v[200:203], v[108:111]
	v_mfma_f32_16x16x32_bf16 v[100:103], v[160:163], v[200:203], v[100:103]
	v_mfma_f32_16x16x32_bf16 v[92:95], v[152:155], v[208:211], v[92:95]
	v_mfma_f32_16x16x32_bf16 v[80:83], v[160:163], v[208:211], v[80:83]
	v_mfma_f32_16x16x32_bf16 v[104:107], v[164:167], v[180:183], v[104:107]
	v_mfma_f32_16x16x32_bf16 v[96:99], v[172:175], v[180:183], v[96:99]
	v_mfma_f32_16x16x32_bf16 v[88:91], v[164:167], v[188:191], v[88:91]
	v_mfma_f32_16x16x32_bf16 v[84:87], v[172:175], v[188:191], v[84:87]
	v_mfma_f32_16x16x32_bf16 v[76:79], v[164:167], v[196:199], v[76:79]
	v_mfma_f32_16x16x32_bf16 v[72:75], v[172:175], v[196:199], v[72:75]
	v_mfma_f32_16x16x32_bf16 v[68:71], v[164:167], v[204:207], v[68:71]
	v_mfma_f32_16x16x32_bf16 v[64:67], v[172:175], v[204:207], v[64:67]
	v_mfma_f32_16x16x32_bf16 v[104:107], v[168:171], v[184:187], v[104:107]
	v_mfma_f32_16x16x32_bf16 v[96:99], v[176:179], v[184:187], v[96:99]
	v_mfma_f32_16x16x32_bf16 v[88:91], v[168:171], v[192:195], v[88:91]
	v_mfma_f32_16x16x32_bf16 v[84:87], v[176:179], v[192:195], v[84:87]
	v_mfma_f32_16x16x32_bf16 v[76:79], v[168:171], v[200:203], v[76:79]
	v_mfma_f32_16x16x32_bf16 v[72:75], v[176:179], v[200:203], v[72:75]
	v_mfma_f32_16x16x32_bf16 v[68:71], v[168:171], v[208:211], v[68:71]
	v_mfma_f32_16x16x32_bf16 v[64:67], v[176:179], v[208:211], v[64:67]
	s_setprio 0
	s_barrier
	s_add_i32 s60, s47, s39
	v_lshl_add_u64 v[144:145], s[34:35], 0, v[128:129]
	s_mov_b32 m0, s60
	ds_read_b128 v[180:183], v151 offset:16384
	ds_read_b128 v[184:187], v151 offset:17408
	ds_read_b128 v[188:191], v151 offset:18432
	ds_read_b128 v[192:195], v151 offset:19456
	ds_read_b128 v[196:199], v151 offset:20480
	ds_read_b128 v[200:203], v151 offset:21504
	ds_read_b128 v[204:207], v151 offset:22528
	ds_read_b128 v[208:211], v151 offset:23552
	global_load_lds_dwordx4 v[144:145], off
	s_add_i32 m0, s60, 0x2000
	s_add_u32 s60, s34, 0x100000
	v_lshl_add_u64 v[212:213], s[34:35], 0, v[130:131]
	s_addc_u32 s61, s35, 0
	s_add_i32 s62, s48, s39
	global_load_lds_dwordx4 v[212:213], off
	v_lshl_add_u64 v[214:215], s[60:61], 0, v[128:129]
	s_mov_b32 m0, s62
	v_lshl_add_u64 v[216:217], s[36:37], 0, v[130:131]
	global_load_lds_dwordx4 v[214:215], off
	v_lshl_add_u64 v[214:215], s[60:61], 0, v[130:131]
	s_add_i32 m0, s62, 0x2000
	s_nop 0
	global_load_lds_dwordx4 v[214:215], off
	v_lshl_add_u64 v[214:215], s[36:37], 0, v[128:129]
	s_mov_b32 m0, s29
	s_nop 0
	global_load_lds_dwordx4 v[214:215], off
	s_mov_b32 m0, s40
	s_nop 0
	global_load_lds_dwordx4 v[216:217], off
	s_waitcnt vmcnt(8)
	s_waitcnt lgkmcnt(0)
	s_barrier
; #define PG8_STAGE(bufoff, gbase, voff) do { _Pragma("unroll") for (int _i = 0; _i < 2; ++_i) \
;         __builtin_amdgcn_global_load_lds((const unsigned*)((const char*)(gbase) + (voff)[_i]), (LAS unsigned*)(lds + (bufoff) + ldsw + _i * 8192), 16, 0, 0); } while (0)
; #define PG8_LDA(dst, b, h) do { _Pragma("unroll") for (int m = 0; m < 4; ++m) _Pragma("unroll") for (int k = 0; k < 2; ++k) dst[m][k] = *(const LAS bf16x8*)(lds + PG8_SA(b, h) + aoff + m * 2048 + k * 1024); } while (0)
; #define PG8_LDB(dst, b, h) do { _Pragma("unroll") for (int n = 0; n < 2; ++n) _Pragma("unroll") for (int k = 0; k < 2; ++k) dst[n][k] = *(const LAS bf16x8*)(lds + PG8_SB(b, h) + boff + n * 2048 + k * 1024); } while (0)
; #define PG8_MMA(ai, bj, At, Bt) do { __builtin_amdgcn_s_setprio(1); _Pragma("unroll") for (int m = 0; m < 4; ++m) _Pragma("unroll") for (int n = 0; n < 2; ++n) _Pragma("unroll") for (int k = 0; k < 2; ++k) \
;         acc[ai][bj][m][n] = __builtin_amdgcn_mfma_f32_16x16x32_bf16(Bt[n][k], At[m][k], acc[ai][bj][m][n], 0, 0, 0); __builtin_amdgcn_s_setprio(0); } while (0)
; #define PG8_WAIT_V(n) asm volatile("s_waitcnt vmcnt(" #n ")" ::: "memory")
; #define PG8_WAIT_L(n) asm volatile("s_waitcnt lgkmcnt(" #n ")" ::: "memory")
; #define PG8_BAR __builtin_amdgcn_s_barrier()
; #define PG8_SCHED __builtin_amdgcn_sched_barrier(0)
; template <class Epi, bool ALIGN_EPI = true, bool SP2 = true>
; DI void gemm_phase(LAS unsigned char* lds, const Gemm g, const StaticOrder& S, const Epi& E) {
;     ...
;             PG8_WAIT_V(8); PG8_WAIT_L(0); PG8_BAR; PG8_MMA(1, 0, At, B0); PG8_MMA(1, 1, At, B1); PG8_BAR; PG8_SCHED;
;             PG8_LDB(B0, 1, 0); PG8_LDB(B1, 1, 1); PG8_SCHED; PG8_LDA(At, 1, 0); PG8_STAGE(PG8_SA(0, 1), a2 + hstepA, voffA);
;             PG8_WAIT_V(8); PG8_WAIT_L(0); PG8_BAR; PG8_MMA(0, 0, At, B0); PG8_MMA(0, 1, At, B1); PG8_BAR; PG8_SCHED;
;             PG8_LDA(At, 1, 1); PG8_STAGE(PG8_SB(1, 0), b3, voffB); PG8_STAGE(PG8_SB(1, 1), b3 + hstepB, voffB); PG8_STAGE(PG8_SA(1, 0), a3, voffA);
	s_setprio 1
	s_waitcnt lgkmcnt(0)
	v_mfma_f32_16x16x32_bf16 v[60:63], v[140:143], v[180:183], v[60:63]
	v_mfma_f32_16x16x32_bf16 v[56:59], v[156:159], v[180:183], v[56:59]
	v_mfma_f32_16x16x32_bf16 v[52:55], v[140:143], v[188:191], v[52:55]
	v_mfma_f32_16x16x32_bf16 v[48:51], v[156:159], v[188:191], v[48:51]
	v_mfma_f32_16x16x32_bf16 v[44:47], v[140:143], v[196:199], v[44:47]
	v_mfma_f32_16x16x32_bf16 v[36:39], v[156:159], v[196:199], v[36:39]
	v_mfma_f32_16x16x32_bf16 v[28:31], v[140:143], v[204:207], v[28:31]
	v_mfma_f32_16x16x32_bf16 v[16:19], v[156:159], v[204:207], v[16:19]
	v_mfma_f32_16x16x32_bf16 v[60:63], v[152:155], v[184:187], v[60:63]
	v_mfma_f32_16x16x32_bf16 v[56:59], v[160:163], v[184:187], v[56:59]
	v_mfma_f32_16x16x32_bf16 v[52:55], v[152:155], v[192:195], v[52:55]
	v_mfma_f32_16x16x32_bf16 v[48:51], v[160:163], v[192:195], v[48:51]
	v_mfma_f32_16x16x32_bf16 v[44:47], v[152:155], v[200:203], v[44:47]
	v_mfma_f32_16x16x32_bf16 v[36:39], v[160:163], v[200:203], v[36:39]
	v_mfma_f32_16x16x32_bf16 v[28:31], v[152:155], v[208:211], v[28:31]
	v_mfma_f32_16x16x32_bf16 v[16:19], v[160:163], v[208:211], v[16:19]
	v_mfma_f32_16x16x32_bf16 v[40:43], v[164:167], v[180:183], v[40:43]
	v_mfma_f32_16x16x32_bf16 v[32:35], v[172:175], v[180:183], v[32:35]
	v_mfma_f32_16x16x32_bf16 v[24:27], v[164:167], v[188:191], v[24:27]
	v_mfma_f32_16x16x32_bf16 v[20:23], v[172:175], v[188:191], v[20:23]
	v_mfma_f32_16x16x32_bf16 v[12:15], v[164:167], v[196:199], v[12:15]
	v_mfma_f32_16x16x32_bf16 v[8:11], v[172:175], v[196:199], v[8:11]
	v_mfma_f32_16x16x32_bf16 v[4:7], v[164:167], v[204:207], v[4:7]
	v_mfma_f32_16x16x32_bf16 v[0:3], v[172:175], v[204:207], v[0:3]
	v_mfma_f32_16x16x32_bf16 v[40:43], v[168:171], v[184:187], v[40:43]
	v_mfma_f32_16x16x32_bf16 v[32:35], v[176:179], v[184:187], v[32:35]
	v_mfma_f32_16x16x32_bf16 v[24:27], v[168:171], v[192:195], v[24:27]
	v_mfma_f32_16x16x32_bf16 v[20:23], v[176:179], v[192:195], v[20:23]
	v_mfma_f32_16x16x32_bf16 v[12:15], v[168:171], v[200:203], v[12:15]
	v_mfma_f32_16x16x32_bf16 v[8:11], v[176:179], v[200:203], v[8:11]
	v_mfma_f32_16x16x32_bf16 v[4:7], v[168:171], v[208:211], v[4:7]
	v_mfma_f32_16x16x32_bf16 v[0:3], v[176:179], v[208:211], v[0:3]
	s_setprio 0
	s_barrier
	s_add_i32 s60, 0, 0x18000
	s_add_i32 s61, 0, 0x1c000
	v_add_u32_e32 v160, s60, v147
	v_add_u32_e32 v176, s61, v147
	ds_read_b128 v[140:143], v160
	ds_read_b128 v[152:155], v160 offset:1024
	ds_read_b128 v[156:159], v160 offset:2048
	ds_read_b128 v[160:163], v160 offset:3072
	ds_read_b128 v[164:167], v176
	ds_read_b128 v[168:171], v176 offset:1024
	ds_read_b128 v[172:175], v176 offset:2048
	ds_read_b128 v[176:179], v176 offset:3072
	s_add_u32 s36, s36, 0x100000
	s_addc_u32 s37, s37, 0
	s_mov_b32 m0, s41
	v_lshl_add_u64 v[218:219], s[36:37], 0, v[128:129]
	ds_read_b128 v[180:183], v151 offset:32768
	ds_read_b128 v[184:187], v151 offset:33792
	ds_read_b128 v[188:191], v151 offset:34816
	ds_read_b128 v[192:195], v151 offset:35840
	ds_read_b128 v[196:199], v151 offset:36864
	ds_read_b128 v[200:203], v151 offset:37888
	ds_read_b128 v[204:207], v151 offset:38912
	ds_read_b128 v[208:211], v151 offset:39936
	global_load_lds_dwordx4 v[218:219], off
	v_lshl_add_u64 v[218:219], s[36:37], 0, v[130:131]
	s_mov_b32 m0, s42
	s_nop 0
	global_load_lds_dwordx4 v[218:219], off
	s_waitcnt vmcnt(8)
	s_waitcnt lgkmcnt(0)
	s_barrier
	s_setprio 1
	s_waitcnt lgkmcnt(0)
	v_mfma_f32_16x16x32_bf16 v[124:127], v[140:143], v[180:183], v[124:127]
	v_mfma_f32_16x16x32_bf16 v[120:123], v[156:159], v[180:183], v[120:123]
	v_mfma_f32_16x16x32_bf16 v[116:119], v[140:143], v[188:191], v[116:119]
	v_mfma_f32_16x16x32_bf16 v[112:115], v[156:159], v[188:191], v[112:115]
	v_mfma_f32_16x16x32_bf16 v[108:111], v[140:143], v[196:199], v[108:111]
	v_mfma_f32_16x16x32_bf16 v[100:103], v[156:159], v[196:199], v[100:103]
	v_mfma_f32_16x16x32_bf16 v[92:95], v[140:143], v[204:207], v[92:95]
	v_mfma_f32_16x16x32_bf16 v[80:83], v[156:159], v[204:207], v[80:83]
	v_mfma_f32_16x16x32_bf16 v[124:127], v[152:155], v[184:187], v[124:127]
	v_mfma_f32_16x16x32_bf16 v[120:123], v[160:163], v[184:187], v[120:123]
	v_mfma_f32_16x16x32_bf16 v[116:119], v[152:155], v[192:195], v[116:119]
	v_mfma_f32_16x16x32_bf16 v[112:115], v[160:163], v[192:195], v[112:115]
	v_mfma_f32_16x16x32_bf16 v[108:111], v[152:155], v[200:203], v[108:111]
	v_mfma_f32_16x16x32_bf16 v[100:103], v[160:163], v[200:203], v[100:103]
	v_mfma_f32_16x16x32_bf16 v[92:95], v[152:155], v[208:211], v[92:95]
	v_mfma_f32_16x16x32_bf16 v[80:83], v[160:163], v[208:211], v[80:83]
	v_mfma_f32_16x16x32_bf16 v[104:107], v[164:167], v[180:183], v[104:107]
	v_mfma_f32_16x16x32_bf16 v[96:99], v[172:175], v[180:183], v[96:99]
	v_mfma_f32_16x16x32_bf16 v[88:91], v[164:167], v[188:191], v[88:91]
	v_mfma_f32_16x16x32_bf16 v[84:87], v[172:175], v[188:191], v[84:87]
	v_mfma_f32_16x16x32_bf16 v[76:79], v[164:167], v[196:199], v[76:79]
	v_mfma_f32_16x16x32_bf16 v[72:75], v[172:175], v[196:199], v[72:75]
	v_mfma_f32_16x16x32_bf16 v[68:71], v[164:167], v[204:207], v[68:71]
	v_mfma_f32_16x16x32_bf16 v[64:67], v[172:175], v[204:207], v[64:67]
	v_mfma_f32_16x16x32_bf16 v[104:107], v[168:171], v[184:187], v[104:107]
	v_mfma_f32_16x16x32_bf16 v[96:99], v[176:179], v[184:187], v[96:99]
	v_mfma_f32_16x16x32_bf16 v[88:91], v[168:171], v[192:195], v[88:91]
	v_mfma_f32_16x16x32_bf16 v[84:87], v[176:179], v[192:195], v[84:87]
	v_mfma_f32_16x16x32_bf16 v[76:79], v[168:171], v[200:203], v[76:79]
	v_mfma_f32_16x16x32_bf16 v[72:75], v[176:179], v[200:203], v[72:75]
	v_mfma_f32_16x16x32_bf16 v[68:71], v[168:171], v[208:211], v[68:71]
	v_mfma_f32_16x16x32_bf16 v[64:67], v[176:179], v[208:211], v[64:67]
	s_setprio 0
	s_barrier
; #define PG8_STAGE(bufoff, gbase, voff) do { _Pragma("unroll") for (int _i = 0; _i < 2; ++_i) \
;         __builtin_amdgcn_global_load_lds((const unsigned*)((const char*)(gbase) + (voff)[_i]), (LAS unsigned*)(lds + (bufoff) + ldsw + _i * 8192), 16, 0, 0); } while (0)
; #define PG8_LDA(dst, b, h) do { _Pragma("unroll") for (int m = 0; m < 4; ++m) _Pragma("unroll") for (int k = 0; k < 2; ++k) dst[m][k] = *(const LAS bf16x8*)(lds + PG8_SA(b, h) + aoff + m * 2048 + k * 1024); } while (0)
; #define PG8_MMA(ai, bj, At, Bt) do { __builtin_amdgcn_s_setprio(1); _Pragma("unroll") for (int m = 0; m < 4; ++m) _Pragma("unroll") for (int n = 0; n < 2; ++n) _Pragma("unroll") for (int k = 0; k < 2; ++k) \
;         acc[ai][bj][m][n] = __builtin_amdgcn_mfma_f32_16x16x32_bf16(Bt[n][k], At[m][k], acc[ai][bj][m][n], 0, 0, 0); __builtin_amdgcn_s_setprio(0); } while (0)
; #define PG8_WAIT_V(n) asm volatile("s_waitcnt vmcnt(" #n ")" ::: "memory")
; #define PG8_WAIT_L(n) asm volatile("s_waitcnt lgkmcnt(" #n ")" ::: "memory")
; #define PG8_BAR __builtin_amdgcn_s_barrier()
; #define PG8_SCHED __builtin_amdgcn_sched_barrier(0)
; template <class Epi, bool ALIGN_EPI = true, bool SP2 = true>
; DI void gemm_phase(LAS unsigned char* lds, const Gemm g, const StaticOrder& S, const Epi& E) {
;     ...
;             PG8_LDA(At, 1, 1); PG8_STAGE(PG8_SB(1, 0), b3, voffB); PG8_STAGE(PG8_SB(1, 1), b3 + hstepB, voffB); PG8_STAGE(PG8_SA(1, 0), a3, voffA);
;             PG8_WAIT_V(8); PG8_WAIT_L(0); PG8_BAR; PG8_MMA(1, 0, At, B0); PG8_MMA(1, 1, At, B1); PG8_BAR; PG8_SCHED;
;     ...
;         if constexpr (ALIGN_EPI) { if (wr == 0) PG8_BAR; }
	s_add_i32 s36, s60, s39
	v_lshl_add_u64 v[144:145], v[144:145], 0, s[6:7]
	s_mov_b32 m0, s36
	ds_read_b128 v[180:183], v151 offset:49152
	ds_read_b128 v[184:187], v151 offset:50176
	ds_read_b128 v[188:191], v151 offset:51200
	ds_read_b128 v[192:195], v151 offset:52224
	ds_read_b128 v[196:199], v151 offset:53248
	ds_read_b128 v[200:203], v151 offset:54272
	ds_read_b128 v[204:207], v151 offset:55296
	ds_read_b128 v[208:211], v151 offset:56320
	global_load_lds_dwordx4 v[144:145], off
	s_add_i32 m0, s36, 0x2000
	s_add_u32 s34, s34, 0x100080
	v_lshl_add_u64 v[144:145], v[212:213], 0, s[6:7]
	s_addc_u32 s35, s35, 0
	s_add_i32 s36, s61, s39
	global_load_lds_dwordx4 v[144:145], off
	v_lshl_add_u64 v[144:145], s[34:35], 0, v[128:129]
	s_mov_b32 m0, s36
	s_nop 0
	global_load_lds_dwordx4 v[144:145], off
	v_lshl_add_u64 v[144:145], s[34:35], 0, v[130:131]
	s_add_i32 m0, s36, 0x2000
	s_nop 0
	global_load_lds_dwordx4 v[144:145], off
	v_lshl_add_u64 v[144:145], v[214:215], 0, s[6:7]
	s_mov_b32 m0, s44
	s_nop 0
	global_load_lds_dwordx4 v[144:145], off
	v_lshl_add_u64 v[144:145], v[216:217], 0, s[6:7]
	s_mov_b32 m0, s45
	s_nop 0
	global_load_lds_dwordx4 v[144:145], off
	s_waitcnt vmcnt(8)
	s_waitcnt lgkmcnt(0)
	s_barrier
	s_setprio 1
	s_waitcnt lgkmcnt(0)
	v_mfma_f32_16x16x32_bf16 v[60:63], v[140:143], v[180:183], v[60:63]
	v_mfma_f32_16x16x32_bf16 v[56:59], v[156:159], v[180:183], v[56:59]
	v_mfma_f32_16x16x32_bf16 v[52:55], v[140:143], v[188:191], v[52:55]
	v_mfma_f32_16x16x32_bf16 v[48:51], v[156:159], v[188:191], v[48:51]
	v_mfma_f32_16x16x32_bf16 v[44:47], v[140:143], v[196:199], v[44:47]
	v_mfma_f32_16x16x32_bf16 v[36:39], v[156:159], v[196:199], v[36:39]
	v_mfma_f32_16x16x32_bf16 v[28:31], v[140:143], v[204:207], v[28:31]
	v_mfma_f32_16x16x32_bf16 v[16:19], v[156:159], v[204:207], v[16:19]
	v_mfma_f32_16x16x32_bf16 v[60:63], v[152:155], v[184:187], v[60:63]
	v_mfma_f32_16x16x32_bf16 v[56:59], v[160:163], v[184:187], v[56:59]
	v_mfma_f32_16x16x32_bf16 v[52:55], v[152:155], v[192:195], v[52:55]
	v_mfma_f32_16x16x32_bf16 v[48:51], v[160:163], v[192:195], v[48:51]
	v_mfma_f32_16x16x32_bf16 v[44:47], v[152:155], v[200:203], v[44:47]
	v_mfma_f32_16x16x32_bf16 v[36:39], v[160:163], v[200:203], v[36:39]
	v_mfma_f32_16x16x32_bf16 v[28:31], v[152:155], v[208:211], v[28:31]
	v_mfma_f32_16x16x32_bf16 v[16:19], v[160:163], v[208:211], v[16:19]
	v_mfma_f32_16x16x32_bf16 v[40:43], v[164:167], v[180:183], v[40:43]
	v_mfma_f32_16x16x32_bf16 v[32:35], v[172:175], v[180:183], v[32:35]
	v_mfma_f32_16x16x32_bf16 v[24:27], v[164:167], v[188:191], v[24:27]
	v_mfma_f32_16x16x32_bf16 v[20:23], v[172:175], v[188:191], v[20:23]
	v_mfma_f32_16x16x32_bf16 v[12:15], v[164:167], v[196:199], v[12:15]
	v_mfma_f32_16x16x32_bf16 v[8:11], v[172:175], v[196:199], v[8:11]
	v_mfma_f32_16x16x32_bf16 v[4:7], v[164:167], v[204:207], v[4:7]
	v_mfma_f32_16x16x32_bf16 v[0:3], v[172:175], v[204:207], v[0:3]
	v_mfma_f32_16x16x32_bf16 v[40:43], v[168:171], v[184:187], v[40:43]
	v_mfma_f32_16x16x32_bf16 v[32:35], v[176:179], v[184:187], v[32:35]
	v_mfma_f32_16x16x32_bf16 v[24:27], v[168:171], v[192:195], v[24:27]
	v_mfma_f32_16x16x32_bf16 v[20:23], v[176:179], v[192:195], v[20:23]
	v_mfma_f32_16x16x32_bf16 v[12:15], v[168:171], v[200:203], v[12:15]
	v_mfma_f32_16x16x32_bf16 v[8:11], v[176:179], v[200:203], v[8:11]
	v_mfma_f32_16x16x32_bf16 v[4:7], v[168:171], v[208:211], v[4:7]
	v_mfma_f32_16x16x32_bf16 v[0:3], v[176:179], v[208:211], v[0:3]
	s_setprio 0
	s_barrier
	s_add_i32 s59, s59, 2
	s_add_u32 s30, s30, 0x100
	s_addc_u32 s31, s31, 0
	s_add_u32 s56, s56, 0x100
	s_addc_u32 s57, s57, 0
	s_cmp_gt_u32 s59, 61
	s_cbranch_scc0 .LBB0_839
	s_and_b64 vcc, exec, s[8:9]
	s_cbranch_vccz .LBB0_842
	s_barrier
